# removed the compiler's preheader s_waitcnt vmcnt(0) drain before each unit's K-loop (6 GEMM loops): epilogue stores now drain under the first K-tile
# speedup vs baseline: 1.0202x; 1.0000x over previous
; #define PG8_STAGE(bufoff, gbase, voff) do { _Pragma("unroll") for (int _i = 0; _i < 2; ++_i) \
;         __builtin_amdgcn_global_load_lds((const unsigned*)((const char*)(gbase) + (voff)[_i]), (LAS unsigned*)(lds + (bufoff) + ldsw + _i * 8192), 16, 0, 0); } while (0)
; #define PG8_LDA(dst, b, h) do { _Pragma("unroll") for (int m = 0; m < 4; ++m) _Pragma("unroll") for (int k = 0; k < 2; ++k) dst[m][k] = *(const LAS bf16x8*)(lds + PG8_SA(b, h) + aoff + m * 2048 + k * 1024); } while (0)
; #define PG8_LDB(dst, b, h) do { _Pragma("unroll") for (int n = 0; n < 2; ++n) _Pragma("unroll") for (int k = 0; k < 2; ++k) dst[n][k] = *(const LAS bf16x8*)(lds + PG8_SB(b, h) + boff + n * 2048 + k * 1024); } while (0)
; #define PG8_WAIT_V(n) asm volatile("s_waitcnt vmcnt(" #n ")" ::: "memory")
; #define PG8_WAIT_L(n) asm volatile("s_waitcnt lgkmcnt(" #n ")" ::: "memory")
; #define PG8_BAR __builtin_amdgcn_s_barrier()
; #define PG8_SCHED __builtin_amdgcn_sched_barrier(0)
; template <class Epi, class Sched>
; __device__ __forceinline__ void gemm_phase(LAS unsigned char* lds, const Gemm g, const Sched& S, const Epi& E) {
;     ...
;         const bool has_next = S.next(ui + 1, nxt);
;         const char* nA = has_next ? (const char*)g.A + (size_t)nxt.pm * tstepA : cA; const char* nB = has_next ? (const char*)g.Bt + (size_t)nxt.pn * tstepB : cB;
;         for (int t = 0; t < nt; t += 2) {
;             const bool last = (t == nt - 2);
;             const char* a1 = cA + (size_t)(t + 1) * kstep;
;             const char* a2 = last ? nA : cA + (size_t)(t + 2) * kstep; const char* b2 = last ? nB : cB + (size_t)(t + 2) * kstep;
;             const char* a3 = a2 + kstep; const char* b3 = b2 + kstep;
;             if (last && has_next) S.a_ready(nxt);
;             PG8_LDB(B0, 0, 0); PG8_SCHED; PG8_LDA(At, 0, 0); PG8_STAGE(PG8_SA(1, 1), a1 + hstepA, voffA);
;             PG8_WAIT_L(8); PG8_BAR; PG8_WAIT_L(0); PG8_MMA(0, 0, At, B0); PG8_BAR; PG8_SCHED;
;             PG8_LDB(B1, 0, 1); PG8_STAGE(PG8_SB(0, 0), b2, voffB);
;             PG8_BAR; PG8_WAIT_L(0); PG8_MMA(0, 1, At, B1); PG8_BAR;
;             PG8_LDA(At, 0, 1); PG8_STAGE(PG8_SA(0, 0), a2, voffA);
;             PG8_BAR; PG8_WAIT_L(0); PG8_MMA(1, 0, At, B0); PG8_BAR; PG8_SCHED;
;             PG8_STAGE(PG8_SB(0, 1), b2 + hstepB, voffB);
;             PG8_WAIT_V(6); PG8_BAR; PG8_MMA(1, 1, At, B1); PG8_BAR;
.LBB0_351:
	v_mov_b64_e32 v[4:5], 0xd80
	s_ashr_i32 s15, s14, 31
	v_cmp_lt_i64_e32 vcc, s[4:5], v[4:5]
	s_lshl_b64 s[4:5], s[14:15], 20
	s_add_u32 s18, s88, s4
	s_addc_u32 s19, s89, s5
	s_and_b64 s[4:5], vcc, exec
	s_cselect_b32 s15, s19, s7
	s_cselect_b32 s51, s18, s6
	s_ashr_i32 s1, s0, 31
	s_lshl_b64 s[4:5], s[0:1], 20
	s_add_u32 s4, s28, s4
	s_addc_u32 s5, s29, s5
	s_and_b64 s[24:25], vcc, exec
	s_cselect_b32 s1, s5, s21
	s_cselect_b32 s52, s4, s20
	s_add_u32 s6, s6, 0x80080
	s_addc_u32 s7, s7, 0
	s_add_u32 s53, s20, 0x100
	s_addc_u32 s54, s21, 0
	s_mov_b32 s55, -2
	s_waitcnt lgkmcnt(0)
	s_setprio 0
	s_add_u32 s20, s6, 0xfff80080
	s_addc_u32 s21, s7, -1
	s_add_i32 s56, 0, 0x10000
	v_add_u32_e32 v2, s56, v1
	ds_read_b128 v[144:147], v2
	ds_read_b128 v[150:153], v2 offset:1024
	ds_read_b128 v[154:157], v2 offset:2048
	ds_read_b128 v[158:161], v2 offset:3072
	s_cmp_eq_u32 s55, 28
	s_cselect_b32 s25, s15, s21
	s_cselect_b32 s24, s51, s20
	s_cselect_b32 s21, s1, s54
	s_cselect_b32 s20, s52, s53
	ds_read_b128 v[162:165], v149
	ds_read_b128 v[166:169], v149 offset:1024
	ds_read_b128 v[170:173], v149 offset:2048
	ds_read_b128 v[174:177], v149 offset:3072
	ds_read_b128 v[178:181], v149 offset:4096
	ds_read_b128 v[182:185], v149 offset:5120
	ds_read_b128 v[186:189], v149 offset:6144
	ds_read_b128 v[190:193], v149 offset:7168
	s_add_i32 s58, 0, 0x14000
	v_add_u32_e32 v2, s58, v1
	ds_read_b128 v[194:197], v2
	ds_read_b128 v[198:201], v2 offset:1024
	ds_read_b128 v[202:205], v2 offset:2048
	ds_read_b128 v[206:209], v2 offset:3072
	s_add_i32 m0, s31, 0xc000
	s_nop 0
	global_load_lds_dwordx4 v140, s[6:7]
	s_add_i32 m0, s31, 0xe000
	s_nop 0
	global_load_lds_dwordx4 v142, s[6:7]
	s_waitcnt lgkmcnt(0)
	s_setprio 1
	s_barrier
	v_mfma_f32_16x16x32_bf16 v[128:131], v[144:147], v[162:165], 0
	v_mfma_f32_16x16x32_bf16 v[124:127], v[154:157], v[162:165], 0
	v_mfma_f32_16x16x32_bf16 v[112:115], v[144:147], v[170:173], 0
	v_mfma_f32_16x16x32_bf16 v[108:111], v[154:157], v[170:173], 0
	v_mfma_f32_16x16x32_bf16 v[96:99], v[144:147], v[178:181], 0
	v_mfma_f32_16x16x32_bf16 v[92:95], v[154:157], v[178:181], 0
	v_mfma_f32_16x16x32_bf16 v[80:83], v[144:147], v[186:189], 0
	v_mfma_f32_16x16x32_bf16 v[76:79], v[154:157], v[186:189], 0
	v_mfma_f32_16x16x32_bf16 v[128:131], v[150:153], v[166:169], v[128:131]
	v_mfma_f32_16x16x32_bf16 v[124:127], v[158:161], v[166:169], v[124:127]
	v_mfma_f32_16x16x32_bf16 v[112:115], v[150:153], v[174:177], v[112:115]
	v_mfma_f32_16x16x32_bf16 v[108:111], v[158:161], v[174:177], v[108:111]
	v_mfma_f32_16x16x32_bf16 v[96:99], v[150:153], v[182:185], v[96:99]
	v_mfma_f32_16x16x32_bf16 v[92:95], v[158:161], v[182:185], v[92:95]
	v_mfma_f32_16x16x32_bf16 v[80:83], v[150:153], v[190:193], v[80:83]
	v_mfma_f32_16x16x32_bf16 v[76:79], v[158:161], v[190:193], v[76:79]
	v_mfma_f32_16x16x32_bf16 v[120:123], v[194:197], v[162:165], 0
	v_mfma_f32_16x16x32_bf16 v[116:119], v[202:205], v[162:165], 0
	v_mfma_f32_16x16x32_bf16 v[104:107], v[194:197], v[170:173], 0
	v_mfma_f32_16x16x32_bf16 v[100:103], v[202:205], v[170:173], 0
	v_mfma_f32_16x16x32_bf16 v[88:91], v[194:197], v[178:181], 0
	v_mfma_f32_16x16x32_bf16 v[84:87], v[202:205], v[178:181], 0
	v_mfma_f32_16x16x32_bf16 v[72:75], v[194:197], v[186:189], 0
	v_mfma_f32_16x16x32_bf16 v[68:71], v[202:205], v[186:189], 0
	v_mfma_f32_16x16x32_bf16 v[120:123], v[198:201], v[166:169], v[120:123]
	v_mfma_f32_16x16x32_bf16 v[116:119], v[206:209], v[166:169], v[116:119]
	v_mfma_f32_16x16x32_bf16 v[104:107], v[198:201], v[174:177], v[104:107]
	v_mfma_f32_16x16x32_bf16 v[100:103], v[206:209], v[174:177], v[100:103]
	v_mfma_f32_16x16x32_bf16 v[88:91], v[198:201], v[182:185], v[88:91]
	v_mfma_f32_16x16x32_bf16 v[84:87], v[206:209], v[182:185], v[84:87]
	v_mfma_f32_16x16x32_bf16 v[72:75], v[198:201], v[190:193], v[72:75]
	v_mfma_f32_16x16x32_bf16 v[68:71], v[206:209], v[190:193], v[68:71]
	s_barrier
	s_setprio 0
	ds_read_b128 v[162:165], v149 offset:16384
	ds_read_b128 v[166:169], v149 offset:17408
	ds_read_b128 v[170:173], v149 offset:18432
	ds_read_b128 v[174:177], v149 offset:19456
	ds_read_b128 v[178:181], v149 offset:20480
	ds_read_b128 v[182:185], v149 offset:21504
	ds_read_b128 v[186:189], v149 offset:22528
	ds_read_b128 v[190:193], v149 offset:23552
	s_add_i32 s56, s56, s30
	v_lshl_add_u64 v[210:211], s[20:21], 0, v[136:137]
	s_mov_b32 m0, s56
	s_nop 0
	global_load_lds_dwordx4 v[210:211], off
	v_lshl_add_u64 v[212:213], s[20:21], 0, v[132:133]
	s_add_i32 m0, s56, 0x2000
	s_nop 0
	global_load_lds_dwordx4 v[212:213], off
	s_mov_b32 m0, s31
	v_lshl_add_u64 v[216:217], s[24:25], 0, v[138:139]
	global_load_lds_dwordx4 v[216:217], off
	v_lshl_add_u64 v[218:219], s[24:25], 0, v[134:135]
	s_mov_b32 m0, s35
	s_nop 0
	global_load_lds_dwordx4 v[218:219], off
	s_add_u32 s56, s20, 0x80000
	s_addc_u32 s57, s21, 0
	s_add_i32 s58, s58, s30
	s_mov_b32 m0, s58
	s_nop 0
	global_load_lds_dwordx4 v136, s[56:57]
	s_add_i32 m0, s58, 0x2000
	s_nop 0
	global_load_lds_dwordx4 v132, s[56:57]
	s_waitcnt lgkmcnt(0)
	s_waitcnt vmcnt(6)
	s_setprio 1
	s_barrier
; #define PG8_STAGE(bufoff, gbase, voff) do { _Pragma("unroll") for (int _i = 0; _i < 2; ++_i) \
;         __builtin_amdgcn_global_load_lds((const unsigned*)((const char*)(gbase) + (voff)[_i]), (LAS unsigned*)(lds + (bufoff) + ldsw + _i * 8192), 16, 0, 0); } while (0)
; #define PG8_LDA(dst, b, h) do { _Pragma("unroll") for (int m = 0; m < 4; ++m) _Pragma("unroll") for (int k = 0; k < 2; ++k) dst[m][k] = *(const LAS bf16x8*)(lds + PG8_SA(b, h) + aoff + m * 2048 + k * 1024); } while (0)
; #define PG8_LDB(dst, b, h) do { _Pragma("unroll") for (int n = 0; n < 2; ++n) _Pragma("unroll") for (int k = 0; k < 2; ++k) dst[n][k] = *(const LAS bf16x8*)(lds + PG8_SB(b, h) + boff + n * 2048 + k * 1024); } while (0)
; #define PG8_MMA(ai, bj, At, Bt) do { __builtin_amdgcn_s_setprio(1); _Pragma("unroll") for (int m = 0; m < 4; ++m) _Pragma("unroll") for (int n = 0; n < 2; ++n) _Pragma("unroll") for (int k = 0; k < 2; ++k) \
;         acc[ai][bj][m][n] = __builtin_amdgcn_mfma_f32_16x16x32_bf16(Bt[n][k], At[m][k], acc[ai][bj][m][n], 0, 0, 0); __builtin_amdgcn_s_setprio(0); } while (0)
; #define PG8_WAIT_V(n) asm volatile("s_waitcnt vmcnt(" #n ")" ::: "memory")
; #define PG8_WAIT_L(n) asm volatile("s_waitcnt lgkmcnt(" #n ")" ::: "memory")
; #define PG8_BAR __builtin_amdgcn_s_barrier()
; #define PG8_SCHED __builtin_amdgcn_sched_barrier(0)
; template <class Epi, class Sched>
; __device__ __forceinline__ void gemm_phase(LAS unsigned char* lds, const Gemm g, const Sched& S, const Epi& E) {
;     ...
;             PG8_BAR; PG8_WAIT_L(0); PG8_MMA(1, 0, At, B0); PG8_BAR; PG8_SCHED;
;             PG8_STAGE(PG8_SB(0, 1), b2 + hstepB, voffB);
;             PG8_WAIT_V(6); PG8_BAR; PG8_MMA(1, 1, At, B1); PG8_BAR;
;             PG8_LDB(B0, 1, 0); PG8_SCHED; PG8_LDA(At, 1, 0); PG8_STAGE(PG8_SA(0, 1), a2 + hstepA, voffA);
;             PG8_WAIT_L(8); PG8_BAR; PG8_WAIT_L(0); PG8_MMA(0, 0, At, B0); PG8_BAR; PG8_SCHED;
;             PG8_LDB(B1, 1, 1); PG8_STAGE(PG8_SB(1, 0), b3, voffB);
;             PG8_BAR; PG8_WAIT_L(0); PG8_MMA(0, 1, At, B1); PG8_BAR;
	v_mfma_f32_16x16x32_bf16 v[64:67], v[144:147], v[162:165], 0
	v_mfma_f32_16x16x32_bf16 v[60:63], v[154:157], v[162:165], 0
	v_mfma_f32_16x16x32_bf16 v[48:51], v[144:147], v[170:173], 0
	v_mfma_f32_16x16x32_bf16 v[44:47], v[154:157], v[170:173], 0
	v_mfma_f32_16x16x32_bf16 v[32:35], v[144:147], v[178:181], 0
	v_mfma_f32_16x16x32_bf16 v[28:31], v[154:157], v[178:181], 0
	v_mfma_f32_16x16x32_bf16 v[16:19], v[144:147], v[186:189], 0
	v_mfma_f32_16x16x32_bf16 v[12:15], v[154:157], v[186:189], 0
	v_mfma_f32_16x16x32_bf16 v[64:67], v[150:153], v[166:169], v[64:67]
	v_mfma_f32_16x16x32_bf16 v[60:63], v[158:161], v[166:169], v[60:63]
	v_mfma_f32_16x16x32_bf16 v[48:51], v[150:153], v[174:177], v[48:51]
	v_mfma_f32_16x16x32_bf16 v[44:47], v[158:161], v[174:177], v[44:47]
	v_mfma_f32_16x16x32_bf16 v[32:35], v[150:153], v[182:185], v[32:35]
	v_mfma_f32_16x16x32_bf16 v[28:31], v[158:161], v[182:185], v[28:31]
	v_mfma_f32_16x16x32_bf16 v[16:19], v[150:153], v[190:193], v[16:19]
	v_mfma_f32_16x16x32_bf16 v[12:15], v[158:161], v[190:193], v[12:15]
	v_mfma_f32_16x16x32_bf16 v[56:59], v[194:197], v[162:165], 0
	v_mfma_f32_16x16x32_bf16 v[52:55], v[202:205], v[162:165], 0
	v_mfma_f32_16x16x32_bf16 v[40:43], v[194:197], v[170:173], 0
	v_mfma_f32_16x16x32_bf16 v[36:39], v[202:205], v[170:173], 0
	v_mfma_f32_16x16x32_bf16 v[24:27], v[194:197], v[178:181], 0
	v_mfma_f32_16x16x32_bf16 v[20:23], v[202:205], v[178:181], 0
	v_mfma_f32_16x16x32_bf16 v[8:11], v[194:197], v[186:189], 0
	v_mfma_f32_16x16x32_bf16 v[4:7], v[202:205], v[186:189], 0
	v_mfma_f32_16x16x32_bf16 v[56:59], v[198:201], v[166:169], v[56:59]
	v_mfma_f32_16x16x32_bf16 v[52:55], v[206:209], v[166:169], v[52:55]
	v_mfma_f32_16x16x32_bf16 v[40:43], v[198:201], v[174:177], v[40:43]
	v_mfma_f32_16x16x32_bf16 v[36:39], v[206:209], v[174:177], v[36:39]
	v_mfma_f32_16x16x32_bf16 v[24:27], v[198:201], v[182:185], v[24:27]
	v_mfma_f32_16x16x32_bf16 v[20:23], v[206:209], v[182:185], v[20:23]
	v_mfma_f32_16x16x32_bf16 v[8:11], v[198:201], v[190:193], v[8:11]
	v_mfma_f32_16x16x32_bf16 v[4:7], v[206:209], v[190:193], v[4:7]
	s_barrier
	s_setprio 0
	s_add_i32 s56, 0, 0x18000
	v_add_u32_e32 v2, s56, v1
	ds_read_b128 v[144:147], v2
	ds_read_b128 v[150:153], v2 offset:1024
	ds_read_b128 v[154:157], v2 offset:2048
	ds_read_b128 v[158:161], v2 offset:3072
	s_add_u32 s24, s24, 0x80000
	s_addc_u32 s25, s25, 0
	ds_read_b128 v[162:165], v149 offset:32768
	ds_read_b128 v[166:169], v149 offset:33792
	ds_read_b128 v[170:173], v149 offset:34816
	ds_read_b128 v[174:177], v149 offset:35840
	ds_read_b128 v[178:181], v149 offset:36864
	ds_read_b128 v[182:185], v149 offset:37888
	ds_read_b128 v[186:189], v149 offset:38912
	ds_read_b128 v[190:193], v149 offset:39936
	s_mov_b32 m0, s36
	s_nop 0
	global_load_lds_dwordx4 v138, s[24:25]
	s_mov_b32 m0, s37
	s_nop 0
	global_load_lds_dwordx4 v134, s[24:25]
	s_add_i32 s24, 0, 0x1c000
	v_add_u32_e32 v2, s24, v1
	ds_read_b128 v[194:197], v2
	ds_read_b128 v[198:201], v2 offset:1024
	ds_read_b128 v[202:205], v2 offset:2048
	ds_read_b128 v[206:209], v2 offset:3072
	s_waitcnt lgkmcnt(0)
	s_setprio 1
	s_barrier
	v_mfma_f32_16x16x32_bf16 v[128:131], v[144:147], v[162:165], v[128:131]
	v_mfma_f32_16x16x32_bf16 v[124:127], v[154:157], v[162:165], v[124:127]
	v_mfma_f32_16x16x32_bf16 v[112:115], v[144:147], v[170:173], v[112:115]
	v_mfma_f32_16x16x32_bf16 v[108:111], v[154:157], v[170:173], v[108:111]
	v_mfma_f32_16x16x32_bf16 v[96:99], v[144:147], v[178:181], v[96:99]
	v_mfma_f32_16x16x32_bf16 v[92:95], v[154:157], v[178:181], v[92:95]
	v_mfma_f32_16x16x32_bf16 v[80:83], v[144:147], v[186:189], v[80:83]
	v_mfma_f32_16x16x32_bf16 v[76:79], v[154:157], v[186:189], v[76:79]
	v_mfma_f32_16x16x32_bf16 v[128:131], v[150:153], v[166:169], v[128:131]
	v_mfma_f32_16x16x32_bf16 v[124:127], v[158:161], v[166:169], v[124:127]
	v_mfma_f32_16x16x32_bf16 v[112:115], v[150:153], v[174:177], v[112:115]
	v_mfma_f32_16x16x32_bf16 v[108:111], v[158:161], v[174:177], v[108:111]
	v_mfma_f32_16x16x32_bf16 v[96:99], v[150:153], v[182:185], v[96:99]
	v_mfma_f32_16x16x32_bf16 v[92:95], v[158:161], v[182:185], v[92:95]
	v_mfma_f32_16x16x32_bf16 v[80:83], v[150:153], v[190:193], v[80:83]
	v_mfma_f32_16x16x32_bf16 v[76:79], v[158:161], v[190:193], v[76:79]
	v_mfma_f32_16x16x32_bf16 v[120:123], v[194:197], v[162:165], v[120:123]
	v_mfma_f32_16x16x32_bf16 v[116:119], v[202:205], v[162:165], v[116:119]
	v_mfma_f32_16x16x32_bf16 v[104:107], v[194:197], v[170:173], v[104:107]
	v_mfma_f32_16x16x32_bf16 v[100:103], v[202:205], v[170:173], v[100:103]
	v_mfma_f32_16x16x32_bf16 v[88:91], v[194:197], v[178:181], v[88:91]
	v_mfma_f32_16x16x32_bf16 v[84:87], v[202:205], v[178:181], v[84:87]
	v_mfma_f32_16x16x32_bf16 v[72:75], v[194:197], v[186:189], v[72:75]
	v_mfma_f32_16x16x32_bf16 v[68:71], v[202:205], v[186:189], v[68:71]
	v_mfma_f32_16x16x32_bf16 v[120:123], v[198:201], v[166:169], v[120:123]
	v_mfma_f32_16x16x32_bf16 v[116:119], v[206:209], v[166:169], v[116:119]
	v_mfma_f32_16x16x32_bf16 v[104:107], v[198:201], v[174:177], v[104:107]
	v_mfma_f32_16x16x32_bf16 v[100:103], v[206:209], v[174:177], v[100:103]
	v_mfma_f32_16x16x32_bf16 v[88:91], v[198:201], v[182:185], v[88:91]
	v_mfma_f32_16x16x32_bf16 v[84:87], v[206:209], v[182:185], v[84:87]
	v_mfma_f32_16x16x32_bf16 v[72:75], v[198:201], v[190:193], v[72:75]
	v_mfma_f32_16x16x32_bf16 v[68:71], v[206:209], v[190:193], v[68:71]
	s_barrier
; #define PG8_STAGE(bufoff, gbase, voff) do { _Pragma("unroll") for (int _i = 0; _i < 2; ++_i) \
;         __builtin_amdgcn_global_load_lds((const unsigned*)((const char*)(gbase) + (voff)[_i]), (LAS unsigned*)(lds + (bufoff) + ldsw + _i * 8192), 16, 0, 0); } while (0)
; #define PG8_LDA(dst, b, h) do { _Pragma("unroll") for (int m = 0; m < 4; ++m) _Pragma("unroll") for (int k = 0; k < 2; ++k) dst[m][k] = *(const LAS bf16x8*)(lds + PG8_SA(b, h) + aoff + m * 2048 + k * 1024); } while (0)
; #define PG8_LDB(dst, b, h) do { _Pragma("unroll") for (int n = 0; n < 2; ++n) _Pragma("unroll") for (int k = 0; k < 2; ++k) dst[n][k] = *(const LAS bf16x8*)(lds + PG8_SB(b, h) + boff + n * 2048 + k * 1024); } while (0)
; #define PG8_MMA(ai, bj, At, Bt) do { __builtin_amdgcn_s_setprio(1); _Pragma("unroll") for (int m = 0; m < 4; ++m) _Pragma("unroll") for (int n = 0; n < 2; ++n) _Pragma("unroll") for (int k = 0; k < 2; ++k) \
;         acc[ai][bj][m][n] = __builtin_amdgcn_mfma_f32_16x16x32_bf16(Bt[n][k], At[m][k], acc[ai][bj][m][n], 0, 0, 0); __builtin_amdgcn_s_setprio(0); } while (0)
; #define PG8_WAIT_V(n) asm volatile("s_waitcnt vmcnt(" #n ")" ::: "memory")
; #define PG8_WAIT_L(n) asm volatile("s_waitcnt lgkmcnt(" #n ")" ::: "memory")
; #define PG8_BAR __builtin_amdgcn_s_barrier()
; #define PG8_SCHED __builtin_amdgcn_sched_barrier(0)
; template <class Epi, class Sched>
; __device__ __forceinline__ void gemm_phase(LAS unsigned char* lds, const Gemm g, const Sched& S, const Epi& E) {
;     ...
;             PG8_LDB(B1, 1, 1); PG8_STAGE(PG8_SB(1, 0), b3, voffB);
;             PG8_BAR; PG8_WAIT_L(0); PG8_MMA(0, 1, At, B1); PG8_BAR;
;             PG8_LDA(At, 1, 1); PG8_STAGE(PG8_SA(1, 0), a3, voffA);
;             PG8_BAR; PG8_WAIT_L(0); PG8_MMA(1, 0, At, B0); PG8_BAR; PG8_SCHED;
;             PG8_STAGE(PG8_SB(1, 1), b3 + hstepB, voffB);
;             PG8_WAIT_V(6); PG8_BAR; PG8_MMA(1, 1, At, B1); PG8_BAR;
	s_setprio 0
	ds_read_b128 v[162:165], v149 offset:49152
	ds_read_b128 v[166:169], v149 offset:50176
	ds_read_b128 v[170:173], v149 offset:51200
	ds_read_b128 v[174:177], v149 offset:52224
	ds_read_b128 v[178:181], v149 offset:53248
	ds_read_b128 v[182:185], v149 offset:54272
	ds_read_b128 v[186:189], v149 offset:55296
	ds_read_b128 v[190:193], v149 offset:56320
	s_add_i32 s25, s56, s30
	v_lshl_add_u64 v[210:211], v[210:211], 0, s[8:9]
	s_mov_b32 m0, s25
	s_nop 0
	global_load_lds_dwordx4 v[210:211], off
	v_lshl_add_u64 v[210:211], v[212:213], 0, s[8:9]
	s_add_i32 m0, s25, 0x2000
	s_nop 0
	global_load_lds_dwordx4 v[210:211], off
	s_mov_b32 m0, s40
	v_lshl_add_u64 v[210:211], v[216:217], 0, s[8:9]
	global_load_lds_dwordx4 v[210:211], off
	v_lshl_add_u64 v[210:211], v[218:219], 0, s[8:9]
	s_mov_b32 m0, s41
	s_nop 0
	global_load_lds_dwordx4 v[210:211], off
	s_add_u32 s20, s20, 0x80080
	s_addc_u32 s21, s21, 0
	s_add_i32 s24, s24, s30
	s_mov_b32 m0, s24
	s_nop 0
	global_load_lds_dwordx4 v136, s[20:21]
	s_add_i32 m0, s24, 0x2000
	s_nop 0
	global_load_lds_dwordx4 v132, s[20:21]
	s_add_i32 s55, s55, 2
	s_add_u32 s6, s6, 0x100
	s_addc_u32 s7, s7, 0
	s_add_u32 s53, s53, 0x100
	s_addc_u32 s54, s54, 0
	s_cmp_gt_u32 s55, 29
	s_waitcnt lgkmcnt(0)
	s_waitcnt vmcnt(6)
	s_setprio 1
	s_barrier
	v_mfma_f32_16x16x32_bf16 v[64:67], v[144:147], v[162:165], v[64:67]
	v_mfma_f32_16x16x32_bf16 v[60:63], v[154:157], v[162:165], v[60:63]
	v_mfma_f32_16x16x32_bf16 v[48:51], v[144:147], v[170:173], v[48:51]
	v_mfma_f32_16x16x32_bf16 v[44:47], v[154:157], v[170:173], v[44:47]
	v_mfma_f32_16x16x32_bf16 v[32:35], v[144:147], v[178:181], v[32:35]
	v_mfma_f32_16x16x32_bf16 v[28:31], v[154:157], v[178:181], v[28:31]
	v_mfma_f32_16x16x32_bf16 v[16:19], v[144:147], v[186:189], v[16:19]
	v_mfma_f32_16x16x32_bf16 v[12:15], v[154:157], v[186:189], v[12:15]
	v_mfma_f32_16x16x32_bf16 v[64:67], v[150:153], v[166:169], v[64:67]
	v_mfma_f32_16x16x32_bf16 v[60:63], v[158:161], v[166:169], v[60:63]
	v_mfma_f32_16x16x32_bf16 v[48:51], v[150:153], v[174:177], v[48:51]
	v_mfma_f32_16x16x32_bf16 v[44:47], v[158:161], v[174:177], v[44:47]
	v_mfma_f32_16x16x32_bf16 v[32:35], v[150:153], v[182:185], v[32:35]
	v_mfma_f32_16x16x32_bf16 v[28:31], v[158:161], v[182:185], v[28:31]
	v_mfma_f32_16x16x32_bf16 v[16:19], v[150:153], v[190:193], v[16:19]
	v_mfma_f32_16x16x32_bf16 v[12:15], v[158:161], v[190:193], v[12:15]
	v_mfma_f32_16x16x32_bf16 v[56:59], v[194:197], v[162:165], v[56:59]
	v_mfma_f32_16x16x32_bf16 v[52:55], v[202:205], v[162:165], v[52:55]
	v_mfma_f32_16x16x32_bf16 v[40:43], v[194:197], v[170:173], v[40:43]
	v_mfma_f32_16x16x32_bf16 v[36:39], v[202:205], v[170:173], v[36:39]
	v_mfma_f32_16x16x32_bf16 v[24:27], v[194:197], v[178:181], v[24:27]
	v_mfma_f32_16x16x32_bf16 v[20:23], v[202:205], v[178:181], v[20:23]
	v_mfma_f32_16x16x32_bf16 v[8:11], v[194:197], v[186:189], v[8:11]
	v_mfma_f32_16x16x32_bf16 v[4:7], v[202:205], v[186:189], v[4:7]
	v_mfma_f32_16x16x32_bf16 v[56:59], v[198:201], v[166:169], v[56:59]
	v_mfma_f32_16x16x32_bf16 v[52:55], v[206:209], v[166:169], v[52:55]
	v_mfma_f32_16x16x32_bf16 v[40:43], v[198:201], v[174:177], v[40:43]
	v_mfma_f32_16x16x32_bf16 v[36:39], v[206:209], v[174:177], v[36:39]
	v_mfma_f32_16x16x32_bf16 v[24:27], v[198:201], v[182:185], v[24:27]
	v_mfma_f32_16x16x32_bf16 v[20:23], v[206:209], v[182:185], v[20:23]
	v_mfma_f32_16x16x32_bf16 v[8:11], v[198:201], v[190:193], v[8:11]
	v_mfma_f32_16x16x32_bf16 v[4:7], v[206:209], v[190:193], v[4:7]
	s_barrier
	s_setprio 0

; #define PG8_STAGE(bufoff, gbase, voff) do { _Pragma("unroll") for (int _i = 0; _i < 2; ++_i) \
;         __builtin_amdgcn_global_load_lds((const unsigned*)((const char*)(gbase) + (voff)[_i]), (LAS unsigned*)(lds + (bufoff) + ldsw + _i * 8192), 16, 0, 0); } while (0)
; #define PG8_LDA(dst, b, h) do { _Pragma("unroll") for (int m = 0; m < 4; ++m) _Pragma("unroll") for (int k = 0; k < 2; ++k) dst[m][k] = *(const LAS bf16x8*)(lds + PG8_SA(b, h) + aoff + m * 2048 + k * 1024); } while (0)
; #define PG8_LDB(dst, b, h) do { _Pragma("unroll") for (int n = 0; n < 2; ++n) _Pragma("unroll") for (int k = 0; k < 2; ++k) dst[n][k] = *(const LAS bf16x8*)(lds + PG8_SB(b, h) + boff + n * 2048 + k * 1024); } while (0)
; #define PG8_WAIT_V(n) asm volatile("s_waitcnt vmcnt(" #n ")" ::: "memory")
; #define PG8_WAIT_L(n) asm volatile("s_waitcnt lgkmcnt(" #n ")" ::: "memory")
; #define PG8_BAR __builtin_amdgcn_s_barrier()
; #define PG8_SCHED __builtin_amdgcn_sched_barrier(0)
; template <class Epi, class Sched>
; __device__ __forceinline__ void gemm_phase(LAS unsigned char* lds, const Gemm g, const Sched& S, const Epi& E) {
;     ...
;         const bool has_next = S.next(ui + 1, nxt);
;         const char* nA = has_next ? (const char*)g.A + (size_t)nxt.pm * tstepA : cA; const char* nB = has_next ? (const char*)g.Bt + (size_t)nxt.pn * tstepB : cB;
;         for (int t = 0; t < nt; t += 2) {
;             const bool last = (t == nt - 2);
;             const char* a1 = cA + (size_t)(t + 1) * kstep;
;             const char* a2 = last ? nA : cA + (size_t)(t + 2) * kstep; const char* b2 = last ? nB : cB + (size_t)(t + 2) * kstep;
;             const char* a3 = a2 + kstep; const char* b3 = b2 + kstep;
;             if (last && has_next) S.a_ready(nxt);
;             PG8_LDB(B0, 0, 0); PG8_SCHED; PG8_LDA(At, 0, 0); PG8_STAGE(PG8_SA(1, 1), a1 + hstepA, voffA);
;             PG8_WAIT_L(8); PG8_BAR; PG8_WAIT_L(0); PG8_MMA(0, 0, At, B0); PG8_BAR; PG8_SCHED;
;             PG8_LDB(B1, 0, 1); PG8_STAGE(PG8_SB(0, 0), b2, voffB);
;             PG8_BAR; PG8_WAIT_L(0); PG8_MMA(0, 1, At, B1); PG8_BAR;
;             PG8_LDA(At, 0, 1); PG8_STAGE(PG8_SA(0, 0), a2, voffA);
;             PG8_BAR; PG8_WAIT_L(0); PG8_MMA(1, 0, At, B0); PG8_BAR; PG8_SCHED;
;             PG8_STAGE(PG8_SB(0, 1), b2 + hstepB, voffB);
;             PG8_WAIT_V(6); PG8_BAR; PG8_MMA(1, 1, At, B1); PG8_BAR;
.LBB0_490:
	s_ashr_i32 s53, s52, 31
	s_lshl_b64 s[18:19], s[52:53], 20
	s_add_u32 s54, s25, s18
	v_cmp_lt_i64_e64 s[14:15], s[14:15], 16
	s_addc_u32 s55, s28, s19
	s_and_b64 s[18:19], s[14:15], exec
	s_cselect_b32 s18, s55, s5
	s_cselect_b32 s19, s54, s4
	s_ashr_i32 s51, s50, 31
	s_lshl_b64 s[56:57], s[50:51], 21
	s_add_u32 s56, s44, s56
	s_addc_u32 s57, s45, s57
	s_and_b64 s[14:15], s[14:15], exec
	s_cselect_b32 s51, s57, s7
	s_cselect_b32 s53, s56, s6
	s_add_u32 s4, s4, 0x80080
	s_addc_u32 s5, s5, 0
	s_add_u32 s65, s6, 0x100
	s_addc_u32 s66, s7, 0
	s_mov_b32 s67, -2
	s_waitcnt lgkmcnt(0)
	s_setprio 0
	s_add_u32 s6, s4, 0xfff80080
	s_addc_u32 s7, s5, -1
	s_add_i32 s68, 0, 0x10000
	v_add_u32_e32 v154, s68, v1
	ds_read_b128 v[142:145], v154
	ds_read_b128 v[146:149], v154 offset:1024
	ds_read_b128 v[150:153], v154 offset:2048
	ds_read_b128 v[158:161], v154 offset:3072
	s_cmp_eq_u32 s67, 60
	s_cselect_b32 s15, s18, s7
	s_cselect_b32 s14, s19, s6
	s_cselect_b32 s7, s51, s66
	s_cselect_b32 s6, s53, s65
	ds_read_b128 v[162:165], v156
	ds_read_b128 v[166:169], v156 offset:1024
	ds_read_b128 v[170:173], v156 offset:2048
	ds_read_b128 v[174:177], v156 offset:3072
	ds_read_b128 v[178:181], v156 offset:4096
	ds_read_b128 v[182:185], v156 offset:5120
	ds_read_b128 v[186:189], v156 offset:6144
	ds_read_b128 v[190:193], v156 offset:7168
	s_add_i32 s70, 0, 0x14000
	v_add_u32_e32 v154, s70, v1
	ds_read_b128 v[194:197], v154
	ds_read_b128 v[198:201], v154 offset:1024
	ds_read_b128 v[202:205], v154 offset:2048
	ds_read_b128 v[206:209], v154 offset:3072
	s_add_i32 m0, s30, 0xc000
	s_nop 0
	global_load_lds_dwordx4 v138, s[4:5]
	s_add_i32 m0, s30, 0xe000
	s_nop 0
	global_load_lds_dwordx4 v140, s[4:5]
	s_waitcnt lgkmcnt(0)
	s_setprio 1
	s_barrier
	v_mfma_f32_16x16x32_bf16 v[128:131], v[142:145], v[162:165], 0
	v_mfma_f32_16x16x32_bf16 v[124:127], v[150:153], v[162:165], 0
	v_mfma_f32_16x16x32_bf16 v[120:123], v[142:145], v[170:173], 0
	v_mfma_f32_16x16x32_bf16 v[116:119], v[150:153], v[170:173], 0
	v_mfma_f32_16x16x32_bf16 v[112:115], v[142:145], v[178:181], 0
	v_mfma_f32_16x16x32_bf16 v[108:111], v[150:153], v[178:181], 0
	v_mfma_f32_16x16x32_bf16 v[104:107], v[142:145], v[186:189], 0
	v_mfma_f32_16x16x32_bf16 v[100:103], v[150:153], v[186:189], 0
	v_mfma_f32_16x16x32_bf16 v[128:131], v[146:149], v[166:169], v[128:131]
	v_mfma_f32_16x16x32_bf16 v[124:127], v[158:161], v[166:169], v[124:127]
	v_mfma_f32_16x16x32_bf16 v[120:123], v[146:149], v[174:177], v[120:123]
	v_mfma_f32_16x16x32_bf16 v[116:119], v[158:161], v[174:177], v[116:119]
	v_mfma_f32_16x16x32_bf16 v[112:115], v[146:149], v[182:185], v[112:115]
	v_mfma_f32_16x16x32_bf16 v[108:111], v[158:161], v[182:185], v[108:111]
	v_mfma_f32_16x16x32_bf16 v[104:107], v[146:149], v[190:193], v[104:107]
	v_mfma_f32_16x16x32_bf16 v[100:103], v[158:161], v[190:193], v[100:103]
	v_mfma_f32_16x16x32_bf16 v[64:67], v[194:197], v[162:165], 0
	v_mfma_f32_16x16x32_bf16 v[60:63], v[202:205], v[162:165], 0
	v_mfma_f32_16x16x32_bf16 v[56:59], v[194:197], v[170:173], 0
	v_mfma_f32_16x16x32_bf16 v[52:55], v[202:205], v[170:173], 0
	v_mfma_f32_16x16x32_bf16 v[48:51], v[194:197], v[178:181], 0
	v_mfma_f32_16x16x32_bf16 v[44:47], v[202:205], v[178:181], 0
	v_mfma_f32_16x16x32_bf16 v[40:43], v[194:197], v[186:189], 0
	v_mfma_f32_16x16x32_bf16 v[36:39], v[202:205], v[186:189], 0
	v_mfma_f32_16x16x32_bf16 v[64:67], v[198:201], v[166:169], v[64:67]
	v_mfma_f32_16x16x32_bf16 v[60:63], v[206:209], v[166:169], v[60:63]
	v_mfma_f32_16x16x32_bf16 v[56:59], v[198:201], v[174:177], v[56:59]
	v_mfma_f32_16x16x32_bf16 v[52:55], v[206:209], v[174:177], v[52:55]
	v_mfma_f32_16x16x32_bf16 v[48:51], v[198:201], v[182:185], v[48:51]
	v_mfma_f32_16x16x32_bf16 v[44:47], v[206:209], v[182:185], v[44:47]
	v_mfma_f32_16x16x32_bf16 v[40:43], v[198:201], v[190:193], v[40:43]
	v_mfma_f32_16x16x32_bf16 v[36:39], v[206:209], v[190:193], v[36:39]
	s_barrier
	s_setprio 0
	ds_read_b128 v[162:165], v156 offset:16384
	ds_read_b128 v[166:169], v156 offset:17408
	ds_read_b128 v[170:173], v156 offset:18432
	ds_read_b128 v[174:177], v156 offset:19456
	ds_read_b128 v[178:181], v156 offset:20480
	ds_read_b128 v[182:185], v156 offset:21504
	ds_read_b128 v[186:189], v156 offset:22528
	ds_read_b128 v[190:193], v156 offset:23552
	s_add_i32 s68, s68, s29
	v_lshl_add_u64 v[154:155], s[6:7], 0, v[2:3]
	s_mov_b32 m0, s68
	v_lshl_add_u64 v[210:211], s[6:7], 0, v[136:137]
	global_load_lds_dwordx4 v[154:155], off
	s_add_i32 m0, s68, 0x2000
	s_nop 0
	global_load_lds_dwordx4 v[210:211], off
	s_mov_b32 m0, s30
	v_lshl_add_u64 v[212:213], s[14:15], 0, v[132:133]
	global_load_lds_dwordx4 v[212:213], off
	v_lshl_add_u64 v[216:217], s[14:15], 0, v[134:135]
	s_mov_b32 m0, s31
	s_nop 0
	global_load_lds_dwordx4 v[216:217], off
	s_add_u32 s68, s6, 0x100000
	s_addc_u32 s69, s7, 0
	s_add_i32 s70, s70, s29
	s_mov_b32 m0, s70
	s_nop 0
	global_load_lds_dwordx4 v2, s[68:69]
	s_add_i32 m0, s70, 0x2000
	s_nop 0
	global_load_lds_dwordx4 v136, s[68:69]
	s_waitcnt lgkmcnt(0)
	s_waitcnt vmcnt(6)
	s_setprio 1
	s_barrier
; #define PG8_STAGE(bufoff, gbase, voff) do { _Pragma("unroll") for (int _i = 0; _i < 2; ++_i) \
;         __builtin_amdgcn_global_load_lds((const unsigned*)((const char*)(gbase) + (voff)[_i]), (LAS unsigned*)(lds + (bufoff) + ldsw + _i * 8192), 16, 0, 0); } while (0)
; #define PG8_LDA(dst, b, h) do { _Pragma("unroll") for (int m = 0; m < 4; ++m) _Pragma("unroll") for (int k = 0; k < 2; ++k) dst[m][k] = *(const LAS bf16x8*)(lds + PG8_SA(b, h) + aoff + m * 2048 + k * 1024); } while (0)
; #define PG8_LDB(dst, b, h) do { _Pragma("unroll") for (int n = 0; n < 2; ++n) _Pragma("unroll") for (int k = 0; k < 2; ++k) dst[n][k] = *(const LAS bf16x8*)(lds + PG8_SB(b, h) + boff + n * 2048 + k * 1024); } while (0)
; #define PG8_MMA(ai, bj, At, Bt) do { __builtin_amdgcn_s_setprio(1); _Pragma("unroll") for (int m = 0; m < 4; ++m) _Pragma("unroll") for (int n = 0; n < 2; ++n) _Pragma("unroll") for (int k = 0; k < 2; ++k) \
;         acc[ai][bj][m][n] = __builtin_amdgcn_mfma_f32_16x16x32_bf16(Bt[n][k], At[m][k], acc[ai][bj][m][n], 0, 0, 0); __builtin_amdgcn_s_setprio(0); } while (0)
; #define PG8_WAIT_V(n) asm volatile("s_waitcnt vmcnt(" #n ")" ::: "memory")
; #define PG8_WAIT_L(n) asm volatile("s_waitcnt lgkmcnt(" #n ")" ::: "memory")
; #define PG8_BAR __builtin_amdgcn_s_barrier()
; #define PG8_SCHED __builtin_amdgcn_sched_barrier(0)
; template <class Epi, class Sched>
; __device__ __forceinline__ void gemm_phase(LAS unsigned char* lds, const Gemm g, const Sched& S, const Epi& E) {
;     ...
;             PG8_BAR; PG8_WAIT_L(0); PG8_MMA(1, 0, At, B0); PG8_BAR; PG8_SCHED;
;             PG8_STAGE(PG8_SB(0, 1), b2 + hstepB, voffB);
;             PG8_WAIT_V(6); PG8_BAR; PG8_MMA(1, 1, At, B1); PG8_BAR;
;             PG8_LDB(B0, 1, 0); PG8_SCHED; PG8_LDA(At, 1, 0); PG8_STAGE(PG8_SA(0, 1), a2 + hstepA, voffA);
;             PG8_WAIT_L(8); PG8_BAR; PG8_WAIT_L(0); PG8_MMA(0, 0, At, B0); PG8_BAR; PG8_SCHED;
;             PG8_LDB(B1, 1, 1); PG8_STAGE(PG8_SB(1, 0), b3, voffB);
;             PG8_BAR; PG8_WAIT_L(0); PG8_MMA(0, 1, At, B1); PG8_BAR;
	v_mfma_f32_16x16x32_bf16 v[96:99], v[142:145], v[162:165], 0
	v_mfma_f32_16x16x32_bf16 v[92:95], v[150:153], v[162:165], 0
	v_mfma_f32_16x16x32_bf16 v[88:91], v[142:145], v[170:173], 0
	v_mfma_f32_16x16x32_bf16 v[84:87], v[150:153], v[170:173], 0
	v_mfma_f32_16x16x32_bf16 v[80:83], v[142:145], v[178:181], 0
	v_mfma_f32_16x16x32_bf16 v[76:79], v[150:153], v[178:181], 0
	v_mfma_f32_16x16x32_bf16 v[72:75], v[142:145], v[186:189], 0
	v_mfma_f32_16x16x32_bf16 v[68:71], v[150:153], v[186:189], 0
	v_mfma_f32_16x16x32_bf16 v[96:99], v[146:149], v[166:169], v[96:99]
	v_mfma_f32_16x16x32_bf16 v[92:95], v[158:161], v[166:169], v[92:95]
	v_mfma_f32_16x16x32_bf16 v[88:91], v[146:149], v[174:177], v[88:91]
	v_mfma_f32_16x16x32_bf16 v[84:87], v[158:161], v[174:177], v[84:87]
	v_mfma_f32_16x16x32_bf16 v[80:83], v[146:149], v[182:185], v[80:83]
	v_mfma_f32_16x16x32_bf16 v[76:79], v[158:161], v[182:185], v[76:79]
	v_mfma_f32_16x16x32_bf16 v[72:75], v[146:149], v[190:193], v[72:75]
	v_mfma_f32_16x16x32_bf16 v[68:71], v[158:161], v[190:193], v[68:71]
	v_mfma_f32_16x16x32_bf16 v[32:35], v[194:197], v[162:165], 0
	v_mfma_f32_16x16x32_bf16 v[28:31], v[202:205], v[162:165], 0
	v_mfma_f32_16x16x32_bf16 v[24:27], v[194:197], v[170:173], 0
	v_mfma_f32_16x16x32_bf16 v[20:23], v[202:205], v[170:173], 0
	v_mfma_f32_16x16x32_bf16 v[16:19], v[194:197], v[178:181], 0
	v_mfma_f32_16x16x32_bf16 v[12:15], v[202:205], v[178:181], 0
	v_mfma_f32_16x16x32_bf16 v[8:11], v[194:197], v[186:189], 0
	v_mfma_f32_16x16x32_bf16 v[4:7], v[202:205], v[186:189], 0
	v_mfma_f32_16x16x32_bf16 v[32:35], v[198:201], v[166:169], v[32:35]
	v_mfma_f32_16x16x32_bf16 v[28:31], v[206:209], v[166:169], v[28:31]
	v_mfma_f32_16x16x32_bf16 v[24:27], v[198:201], v[174:177], v[24:27]
	v_mfma_f32_16x16x32_bf16 v[20:23], v[206:209], v[174:177], v[20:23]
	v_mfma_f32_16x16x32_bf16 v[16:19], v[198:201], v[182:185], v[16:19]
	v_mfma_f32_16x16x32_bf16 v[12:15], v[206:209], v[182:185], v[12:15]
	v_mfma_f32_16x16x32_bf16 v[8:11], v[198:201], v[190:193], v[8:11]
	v_mfma_f32_16x16x32_bf16 v[4:7], v[206:209], v[190:193], v[4:7]
	s_barrier
	s_setprio 0
	s_add_i32 s68, 0, 0x18000
	v_add_u32_e32 v157, s68, v1
	ds_read_b128 v[142:145], v157
	ds_read_b128 v[146:149], v157 offset:1024
	ds_read_b128 v[150:153], v157 offset:2048
	ds_read_b128 v[158:161], v157 offset:3072
	s_add_u32 s14, s14, 0x80000
	s_addc_u32 s15, s15, 0
	ds_read_b128 v[162:165], v156 offset:32768
	ds_read_b128 v[166:169], v156 offset:33792
	ds_read_b128 v[170:173], v156 offset:34816
	ds_read_b128 v[174:177], v156 offset:35840
	ds_read_b128 v[178:181], v156 offset:36864
	ds_read_b128 v[182:185], v156 offset:37888
	ds_read_b128 v[186:189], v156 offset:38912
	ds_read_b128 v[190:193], v156 offset:39936
	s_mov_b32 m0, s38
	s_nop 0
	global_load_lds_dwordx4 v132, s[14:15]
	s_mov_b32 m0, s39
	s_nop 0
	global_load_lds_dwordx4 v134, s[14:15]
	s_add_i32 s14, 0, 0x1c000
	v_add_u32_e32 v157, s14, v1
	ds_read_b128 v[194:197], v157
	ds_read_b128 v[198:201], v157 offset:1024
	ds_read_b128 v[202:205], v157 offset:2048
	ds_read_b128 v[206:209], v157 offset:3072
	s_waitcnt lgkmcnt(0)
	s_setprio 1
	s_barrier
	v_mfma_f32_16x16x32_bf16 v[128:131], v[142:145], v[162:165], v[128:131]
	v_mfma_f32_16x16x32_bf16 v[124:127], v[150:153], v[162:165], v[124:127]
	v_mfma_f32_16x16x32_bf16 v[120:123], v[142:145], v[170:173], v[120:123]
	v_mfma_f32_16x16x32_bf16 v[116:119], v[150:153], v[170:173], v[116:119]
	v_mfma_f32_16x16x32_bf16 v[112:115], v[142:145], v[178:181], v[112:115]
	v_mfma_f32_16x16x32_bf16 v[108:111], v[150:153], v[178:181], v[108:111]
	v_mfma_f32_16x16x32_bf16 v[104:107], v[142:145], v[186:189], v[104:107]
	v_mfma_f32_16x16x32_bf16 v[100:103], v[150:153], v[186:189], v[100:103]
	v_mfma_f32_16x16x32_bf16 v[128:131], v[146:149], v[166:169], v[128:131]
	v_mfma_f32_16x16x32_bf16 v[124:127], v[158:161], v[166:169], v[124:127]
	v_mfma_f32_16x16x32_bf16 v[120:123], v[146:149], v[174:177], v[120:123]
	v_mfma_f32_16x16x32_bf16 v[116:119], v[158:161], v[174:177], v[116:119]
	v_mfma_f32_16x16x32_bf16 v[112:115], v[146:149], v[182:185], v[112:115]
	v_mfma_f32_16x16x32_bf16 v[108:111], v[158:161], v[182:185], v[108:111]
	v_mfma_f32_16x16x32_bf16 v[104:107], v[146:149], v[190:193], v[104:107]
	v_mfma_f32_16x16x32_bf16 v[100:103], v[158:161], v[190:193], v[100:103]
	v_mfma_f32_16x16x32_bf16 v[64:67], v[194:197], v[162:165], v[64:67]
	v_mfma_f32_16x16x32_bf16 v[60:63], v[202:205], v[162:165], v[60:63]
	v_mfma_f32_16x16x32_bf16 v[56:59], v[194:197], v[170:173], v[56:59]
	v_mfma_f32_16x16x32_bf16 v[52:55], v[202:205], v[170:173], v[52:55]
	v_mfma_f32_16x16x32_bf16 v[48:51], v[194:197], v[178:181], v[48:51]
	v_mfma_f32_16x16x32_bf16 v[44:47], v[202:205], v[178:181], v[44:47]
	v_mfma_f32_16x16x32_bf16 v[40:43], v[194:197], v[186:189], v[40:43]
	v_mfma_f32_16x16x32_bf16 v[36:39], v[202:205], v[186:189], v[36:39]
	v_mfma_f32_16x16x32_bf16 v[64:67], v[198:201], v[166:169], v[64:67]
	v_mfma_f32_16x16x32_bf16 v[60:63], v[206:209], v[166:169], v[60:63]
	v_mfma_f32_16x16x32_bf16 v[56:59], v[198:201], v[174:177], v[56:59]
	v_mfma_f32_16x16x32_bf16 v[52:55], v[206:209], v[174:177], v[52:55]
	v_mfma_f32_16x16x32_bf16 v[48:51], v[198:201], v[182:185], v[48:51]
	v_mfma_f32_16x16x32_bf16 v[44:47], v[206:209], v[182:185], v[44:47]
	v_mfma_f32_16x16x32_bf16 v[40:43], v[198:201], v[190:193], v[40:43]
	v_mfma_f32_16x16x32_bf16 v[36:39], v[206:209], v[190:193], v[36:39]
	s_barrier
; #define PG8_STAGE(bufoff, gbase, voff) do { _Pragma("unroll") for (int _i = 0; _i < 2; ++_i) \
;         __builtin_amdgcn_global_load_lds((const unsigned*)((const char*)(gbase) + (voff)[_i]), (LAS unsigned*)(lds + (bufoff) + ldsw + _i * 8192), 16, 0, 0); } while (0)
; #define PG8_LDA(dst, b, h) do { _Pragma("unroll") for (int m = 0; m < 4; ++m) _Pragma("unroll") for (int k = 0; k < 2; ++k) dst[m][k] = *(const LAS bf16x8*)(lds + PG8_SA(b, h) + aoff + m * 2048 + k * 1024); } while (0)
; #define PG8_LDB(dst, b, h) do { _Pragma("unroll") for (int n = 0; n < 2; ++n) _Pragma("unroll") for (int k = 0; k < 2; ++k) dst[n][k] = *(const LAS bf16x8*)(lds + PG8_SB(b, h) + boff + n * 2048 + k * 1024); } while (0)
; #define PG8_MMA(ai, bj, At, Bt) do { __builtin_amdgcn_s_setprio(1); _Pragma("unroll") for (int m = 0; m < 4; ++m) _Pragma("unroll") for (int n = 0; n < 2; ++n) _Pragma("unroll") for (int k = 0; k < 2; ++k) \
;         acc[ai][bj][m][n] = __builtin_amdgcn_mfma_f32_16x16x32_bf16(Bt[n][k], At[m][k], acc[ai][bj][m][n], 0, 0, 0); __builtin_amdgcn_s_setprio(0); } while (0)
; #define PG8_WAIT_V(n) asm volatile("s_waitcnt vmcnt(" #n ")" ::: "memory")
; #define PG8_WAIT_L(n) asm volatile("s_waitcnt lgkmcnt(" #n ")" ::: "memory")
; #define PG8_BAR __builtin_amdgcn_s_barrier()
; #define PG8_SCHED __builtin_amdgcn_sched_barrier(0)
; template <class Epi, class Sched>
; __device__ __forceinline__ void gemm_phase(LAS unsigned char* lds, const Gemm g, const Sched& S, const Epi& E) {
;     ...
;             PG8_LDB(B1, 1, 1); PG8_STAGE(PG8_SB(1, 0), b3, voffB);
;             PG8_BAR; PG8_WAIT_L(0); PG8_MMA(0, 1, At, B1); PG8_BAR;
;             PG8_LDA(At, 1, 1); PG8_STAGE(PG8_SA(1, 0), a3, voffA);
;             PG8_BAR; PG8_WAIT_L(0); PG8_MMA(1, 0, At, B0); PG8_BAR; PG8_SCHED;
;             PG8_STAGE(PG8_SB(1, 1), b3 + hstepB, voffB);
;             PG8_WAIT_V(6); PG8_BAR; PG8_MMA(1, 1, At, B1); PG8_BAR;
	s_setprio 0
	ds_read_b128 v[162:165], v156 offset:49152
	ds_read_b128 v[166:169], v156 offset:50176
	ds_read_b128 v[170:173], v156 offset:51200
	ds_read_b128 v[174:177], v156 offset:52224
	ds_read_b128 v[178:181], v156 offset:53248
	ds_read_b128 v[182:185], v156 offset:54272
	ds_read_b128 v[186:189], v156 offset:55296
	ds_read_b128 v[190:193], v156 offset:56320
	s_add_i32 s15, s68, s29
	v_lshl_add_u64 v[154:155], v[154:155], 0, s[8:9]
	s_mov_b32 m0, s15
	s_nop 0
	global_load_lds_dwordx4 v[154:155], off
	v_lshl_add_u64 v[154:155], v[210:211], 0, s[8:9]
	s_add_i32 m0, s15, 0x2000
	s_nop 0
	global_load_lds_dwordx4 v[154:155], off
	s_mov_b32 m0, s62
	v_lshl_add_u64 v[154:155], v[212:213], 0, s[8:9]
	global_load_lds_dwordx4 v[154:155], off
	v_lshl_add_u64 v[154:155], v[216:217], 0, s[8:9]
	s_mov_b32 m0, s63
	s_nop 0
	global_load_lds_dwordx4 v[154:155], off
	s_add_u32 s6, s6, 0x100080
	s_addc_u32 s7, s7, 0
	s_add_i32 s14, s14, s29
	s_mov_b32 m0, s14
	s_nop 0
	global_load_lds_dwordx4 v2, s[6:7]
	s_add_i32 m0, s14, 0x2000
	s_nop 0
	global_load_lds_dwordx4 v136, s[6:7]
	s_add_i32 s67, s67, 2
	s_add_u32 s4, s4, 0x100
	s_addc_u32 s5, s5, 0
	s_add_u32 s65, s65, 0x100
	s_addc_u32 s66, s66, 0
	s_cmp_gt_u32 s67, 61
	s_waitcnt lgkmcnt(0)
	s_waitcnt vmcnt(6)
	s_setprio 1
	s_barrier
	v_mfma_f32_16x16x32_bf16 v[96:99], v[142:145], v[162:165], v[96:99]
	v_mfma_f32_16x16x32_bf16 v[92:95], v[150:153], v[162:165], v[92:95]
	v_mfma_f32_16x16x32_bf16 v[88:91], v[142:145], v[170:173], v[88:91]
	v_mfma_f32_16x16x32_bf16 v[84:87], v[150:153], v[170:173], v[84:87]
	v_mfma_f32_16x16x32_bf16 v[80:83], v[142:145], v[178:181], v[80:83]
	v_mfma_f32_16x16x32_bf16 v[76:79], v[150:153], v[178:181], v[76:79]
	v_mfma_f32_16x16x32_bf16 v[72:75], v[142:145], v[186:189], v[72:75]
	v_mfma_f32_16x16x32_bf16 v[68:71], v[150:153], v[186:189], v[68:71]
	v_mfma_f32_16x16x32_bf16 v[96:99], v[146:149], v[166:169], v[96:99]
	v_mfma_f32_16x16x32_bf16 v[92:95], v[158:161], v[166:169], v[92:95]
	v_mfma_f32_16x16x32_bf16 v[88:91], v[146:149], v[174:177], v[88:91]
	v_mfma_f32_16x16x32_bf16 v[84:87], v[158:161], v[174:177], v[84:87]
	v_mfma_f32_16x16x32_bf16 v[80:83], v[146:149], v[182:185], v[80:83]
	v_mfma_f32_16x16x32_bf16 v[76:79], v[158:161], v[182:185], v[76:79]
	v_mfma_f32_16x16x32_bf16 v[72:75], v[146:149], v[190:193], v[72:75]
	v_mfma_f32_16x16x32_bf16 v[68:71], v[158:161], v[190:193], v[68:71]
	v_mfma_f32_16x16x32_bf16 v[32:35], v[194:197], v[162:165], v[32:35]
	v_mfma_f32_16x16x32_bf16 v[28:31], v[202:205], v[162:165], v[28:31]
	v_mfma_f32_16x16x32_bf16 v[24:27], v[194:197], v[170:173], v[24:27]
	v_mfma_f32_16x16x32_bf16 v[20:23], v[202:205], v[170:173], v[20:23]
	v_mfma_f32_16x16x32_bf16 v[16:19], v[194:197], v[178:181], v[16:19]
	v_mfma_f32_16x16x32_bf16 v[12:15], v[202:205], v[178:181], v[12:15]
	v_mfma_f32_16x16x32_bf16 v[8:11], v[194:197], v[186:189], v[8:11]
	v_mfma_f32_16x16x32_bf16 v[4:7], v[202:205], v[186:189], v[4:7]
	v_mfma_f32_16x16x32_bf16 v[32:35], v[198:201], v[166:169], v[32:35]
	v_mfma_f32_16x16x32_bf16 v[28:31], v[206:209], v[166:169], v[28:31]
	v_mfma_f32_16x16x32_bf16 v[24:27], v[198:201], v[174:177], v[24:27]
	v_mfma_f32_16x16x32_bf16 v[20:23], v[206:209], v[174:177], v[20:23]
	v_mfma_f32_16x16x32_bf16 v[16:19], v[198:201], v[182:185], v[16:19]
	v_mfma_f32_16x16x32_bf16 v[12:15], v[206:209], v[182:185], v[12:15]
	v_mfma_f32_16x16x32_bf16 v[8:11], v[198:201], v[190:193], v[8:11]
	v_mfma_f32_16x16x32_bf16 v[4:7], v[206:209], v[190:193], v[4:7]
	s_barrier
	s_setprio 0

; #define PG8_STAGE(bufoff, gbase, voff) do { _Pragma("unroll") for (int _i = 0; _i < 2; ++_i) \
;         __builtin_amdgcn_global_load_lds((const unsigned*)((const char*)(gbase) + (voff)[_i]), (LAS unsigned*)(lds + (bufoff) + ldsw + _i * 8192), 16, 0, 0); } while (0)
; #define PG8_LDA(dst, b, h) do { _Pragma("unroll") for (int m = 0; m < 4; ++m) _Pragma("unroll") for (int k = 0; k < 2; ++k) dst[m][k] = *(const LAS bf16x8*)(lds + PG8_SA(b, h) + aoff + m * 2048 + k * 1024); } while (0)
; #define PG8_LDB(dst, b, h) do { _Pragma("unroll") for (int n = 0; n < 2; ++n) _Pragma("unroll") for (int k = 0; k < 2; ++k) dst[n][k] = *(const LAS bf16x8*)(lds + PG8_SB(b, h) + boff + n * 2048 + k * 1024); } while (0)
; #define PG8_WAIT_V(n) asm volatile("s_waitcnt vmcnt(" #n ")" ::: "memory")
; #define PG8_WAIT_L(n) asm volatile("s_waitcnt lgkmcnt(" #n ")" ::: "memory")
; #define PG8_BAR __builtin_amdgcn_s_barrier()
; #define PG8_SCHED __builtin_amdgcn_sched_barrier(0)
; template <class Epi, class Sched>
; __device__ __forceinline__ void gemm_phase(LAS unsigned char* lds, const Gemm g, const Sched& S, const Epi& E) {
;     ...
;         const bool has_next = S.next(ui + 1, nxt);
;         const char* nA = has_next ? (const char*)g.A + (size_t)nxt.pm * tstepA : cA; const char* nB = has_next ? (const char*)g.Bt + (size_t)nxt.pn * tstepB : cB;
;         for (int t = 0; t < nt; t += 2) {
;             const bool last = (t == nt - 2);
;             const char* a1 = cA + (size_t)(t + 1) * kstep;
;             const char* a2 = last ? nA : cA + (size_t)(t + 2) * kstep; const char* b2 = last ? nB : cB + (size_t)(t + 2) * kstep;
;             const char* a3 = a2 + kstep; const char* b3 = b2 + kstep;
;             if (last && has_next) S.a_ready(nxt);
;             PG8_LDB(B0, 0, 0); PG8_SCHED; PG8_LDA(At, 0, 0); PG8_STAGE(PG8_SA(1, 1), a1 + hstepA, voffA);
;             PG8_WAIT_L(8); PG8_BAR; PG8_WAIT_L(0); PG8_MMA(0, 0, At, B0); PG8_BAR; PG8_SCHED;
;             PG8_LDB(B1, 0, 1); PG8_STAGE(PG8_SB(0, 0), b2, voffB);
;             PG8_BAR; PG8_WAIT_L(0); PG8_MMA(0, 1, At, B1); PG8_BAR;
;             PG8_LDA(At, 0, 1); PG8_STAGE(PG8_SA(0, 0), a2, voffA);
;             PG8_BAR; PG8_WAIT_L(0); PG8_MMA(1, 0, At, B0); PG8_BAR; PG8_SCHED;
;             PG8_STAGE(PG8_SB(0, 1), b2 + hstepB, voffB);
;             PG8_WAIT_V(6); PG8_BAR; PG8_MMA(1, 1, At, B1); PG8_BAR;
.LBB0_965:
	v_mov_b64_e32 v[4:5], 0x400
	s_ashr_i32 s15, s14, 31
	v_cmp_lt_i64_e32 vcc, s[4:5], v[4:5]
	s_lshl_b64 s[4:5], s[14:15], 20
	v_readlane_b32 s48, v252, 0
	v_readlane_b32 s49, v252, 1
	s_add_u32 s4, s48, s4
	s_addc_u32 s5, s49, s5
	s_and_b64 s[18:19], vcc, exec
	s_cselect_b32 s15, s5, s7
	s_cselect_b32 s47, s4, s6
	s_ashr_i32 s1, s0, 31
	s_lshl_b64 s[18:19], s[0:1], 20
	s_add_u32 s18, s28, s18
	s_addc_u32 s19, s29, s19
	s_and_b64 s[24:25], vcc, exec
	s_cselect_b32 s1, s19, s21
	s_cselect_b32 s48, s18, s20
	s_add_u32 s6, s6, 0x80080
	s_addc_u32 s7, s7, 0
	v_readlane_b32 s50, v252, 2
	v_readlane_b32 s51, v252, 3
	s_add_u32 s49, s20, 0x100
	s_addc_u32 s50, s21, 0
	s_mov_b32 s51, -2
	s_waitcnt lgkmcnt(0)
	s_setprio 0
	s_add_u32 s20, s6, 0xfff80080
	s_addc_u32 s21, s7, -1
	s_add_i32 s52, 0, 0x10000
	v_add_u32_e32 v144, s52, v1
	ds_read_b128 v[132:135], v144
	ds_read_b128 v[136:139], v144 offset:1024
	ds_read_b128 v[140:143], v144 offset:2048
	ds_read_b128 v[144:147], v144 offset:3072
	s_cmp_eq_u32 s51, 28
	s_cselect_b32 s25, s15, s21
	s_cselect_b32 s24, s47, s20
	s_cselect_b32 s21, s1, s50
	s_cselect_b32 s20, s48, s49
	ds_read_b128 v[148:151], v224
	ds_read_b128 v[152:155], v224 offset:1024
	ds_read_b128 v[156:159], v224 offset:2048
	ds_read_b128 v[160:163], v224 offset:3072
	ds_read_b128 v[164:167], v224 offset:4096
	ds_read_b128 v[168:171], v224 offset:5120
	ds_read_b128 v[172:175], v224 offset:6144
	ds_read_b128 v[176:179], v224 offset:7168
	s_add_i32 s54, 0, 0x14000
	v_add_u32_e32 v202, s54, v1
	ds_read_b128 v[180:183], v202
	ds_read_b128 v[184:187], v202 offset:1024
	ds_read_b128 v[188:191], v202 offset:2048
	ds_read_b128 v[202:205], v202 offset:3072
	s_add_i32 m0, s31, 0xc000
	s_nop 0
	global_load_lds_dwordx4 v198, s[6:7]
	s_add_i32 m0, s31, 0xe000
	s_nop 0
	global_load_lds_dwordx4 v200, s[6:7]
	s_waitcnt lgkmcnt(0)
	s_setprio 1
	s_barrier
	v_mfma_f32_16x16x32_bf16 v[128:131], v[132:135], v[148:151], 0
	v_mfma_f32_16x16x32_bf16 v[124:127], v[140:143], v[148:151], 0
	v_mfma_f32_16x16x32_bf16 v[112:115], v[132:135], v[156:159], 0
	v_mfma_f32_16x16x32_bf16 v[108:111], v[140:143], v[156:159], 0
	v_mfma_f32_16x16x32_bf16 v[100:103], v[132:135], v[164:167], 0
	v_mfma_f32_16x16x32_bf16 v[92:95], v[140:143], v[164:167], 0
	v_mfma_f32_16x16x32_bf16 v[84:87], v[132:135], v[172:175], 0
	v_mfma_f32_16x16x32_bf16 v[76:79], v[140:143], v[172:175], 0
	v_mfma_f32_16x16x32_bf16 v[128:131], v[136:139], v[152:155], v[128:131]
	v_mfma_f32_16x16x32_bf16 v[124:127], v[144:147], v[152:155], v[124:127]
	v_mfma_f32_16x16x32_bf16 v[112:115], v[136:139], v[160:163], v[112:115]
	v_mfma_f32_16x16x32_bf16 v[108:111], v[144:147], v[160:163], v[108:111]
	v_mfma_f32_16x16x32_bf16 v[100:103], v[136:139], v[168:171], v[100:103]
	v_mfma_f32_16x16x32_bf16 v[92:95], v[144:147], v[168:171], v[92:95]
	v_mfma_f32_16x16x32_bf16 v[84:87], v[136:139], v[176:179], v[84:87]
	v_mfma_f32_16x16x32_bf16 v[76:79], v[144:147], v[176:179], v[76:79]
	v_mfma_f32_16x16x32_bf16 v[120:123], v[180:183], v[148:151], 0
	v_mfma_f32_16x16x32_bf16 v[116:119], v[188:191], v[148:151], 0
	v_mfma_f32_16x16x32_bf16 v[104:107], v[180:183], v[156:159], 0
	v_mfma_f32_16x16x32_bf16 v[96:99], v[188:191], v[156:159], 0
	v_mfma_f32_16x16x32_bf16 v[88:91], v[180:183], v[164:167], 0
	v_mfma_f32_16x16x32_bf16 v[80:83], v[188:191], v[164:167], 0
	v_mfma_f32_16x16x32_bf16 v[72:75], v[180:183], v[172:175], 0
	v_mfma_f32_16x16x32_bf16 v[68:71], v[188:191], v[172:175], 0
	v_mfma_f32_16x16x32_bf16 v[120:123], v[184:187], v[152:155], v[120:123]
	v_mfma_f32_16x16x32_bf16 v[116:119], v[202:205], v[152:155], v[116:119]
	v_mfma_f32_16x16x32_bf16 v[104:107], v[184:187], v[160:163], v[104:107]
	v_mfma_f32_16x16x32_bf16 v[96:99], v[202:205], v[160:163], v[96:99]
	v_mfma_f32_16x16x32_bf16 v[88:91], v[184:187], v[168:171], v[88:91]
	v_mfma_f32_16x16x32_bf16 v[80:83], v[202:205], v[168:171], v[80:83]
	v_mfma_f32_16x16x32_bf16 v[72:75], v[184:187], v[176:179], v[72:75]
	v_mfma_f32_16x16x32_bf16 v[68:71], v[202:205], v[176:179], v[68:71]
	s_barrier
	s_setprio 0
	ds_read_b128 v[148:151], v224 offset:16384
	ds_read_b128 v[152:155], v224 offset:17408
	ds_read_b128 v[156:159], v224 offset:18432
	ds_read_b128 v[160:163], v224 offset:19456
	ds_read_b128 v[164:167], v224 offset:20480
	ds_read_b128 v[168:171], v224 offset:21504
	ds_read_b128 v[172:175], v224 offset:22528
	ds_read_b128 v[176:179], v224 offset:23552
	s_add_i32 s52, s52, s30
	v_lshl_add_u64 v[206:207], s[20:21], 0, v[2:3]
	s_mov_b32 m0, s52
	s_nop 0
	global_load_lds_dwordx4 v[206:207], off
	v_lshl_add_u64 v[208:209], s[20:21], 0, v[192:193]
	s_add_i32 m0, s52, 0x2000
	s_nop 0
	global_load_lds_dwordx4 v[208:209], off
	s_mov_b32 m0, s31
	v_lshl_add_u64 v[210:211], s[24:25], 0, v[196:197]
	global_load_lds_dwordx4 v[210:211], off
	v_lshl_add_u64 v[212:213], s[24:25], 0, v[194:195]
	s_mov_b32 m0, s35
	s_nop 0
	global_load_lds_dwordx4 v[212:213], off
	s_add_u32 s52, s20, 0x80000
	s_addc_u32 s53, s21, 0
	s_add_i32 s54, s54, s30
	s_mov_b32 m0, s54
	s_nop 0
	global_load_lds_dwordx4 v2, s[52:53]
	s_add_i32 m0, s54, 0x2000
	s_nop 0
	global_load_lds_dwordx4 v192, s[52:53]
	s_waitcnt lgkmcnt(0)
	s_waitcnt vmcnt(6)
	s_setprio 1
	s_barrier
; #define PG8_STAGE(bufoff, gbase, voff) do { _Pragma("unroll") for (int _i = 0; _i < 2; ++_i) \
;         __builtin_amdgcn_global_load_lds((const unsigned*)((const char*)(gbase) + (voff)[_i]), (LAS unsigned*)(lds + (bufoff) + ldsw + _i * 8192), 16, 0, 0); } while (0)
; #define PG8_LDA(dst, b, h) do { _Pragma("unroll") for (int m = 0; m < 4; ++m) _Pragma("unroll") for (int k = 0; k < 2; ++k) dst[m][k] = *(const LAS bf16x8*)(lds + PG8_SA(b, h) + aoff + m * 2048 + k * 1024); } while (0)
; #define PG8_LDB(dst, b, h) do { _Pragma("unroll") for (int n = 0; n < 2; ++n) _Pragma("unroll") for (int k = 0; k < 2; ++k) dst[n][k] = *(const LAS bf16x8*)(lds + PG8_SB(b, h) + boff + n * 2048 + k * 1024); } while (0)
; #define PG8_MMA(ai, bj, At, Bt) do { __builtin_amdgcn_s_setprio(1); _Pragma("unroll") for (int m = 0; m < 4; ++m) _Pragma("unroll") for (int n = 0; n < 2; ++n) _Pragma("unroll") for (int k = 0; k < 2; ++k) \
;         acc[ai][bj][m][n] = __builtin_amdgcn_mfma_f32_16x16x32_bf16(Bt[n][k], At[m][k], acc[ai][bj][m][n], 0, 0, 0); __builtin_amdgcn_s_setprio(0); } while (0)
; #define PG8_WAIT_V(n) asm volatile("s_waitcnt vmcnt(" #n ")" ::: "memory")
; #define PG8_WAIT_L(n) asm volatile("s_waitcnt lgkmcnt(" #n ")" ::: "memory")
; #define PG8_BAR __builtin_amdgcn_s_barrier()
; #define PG8_SCHED __builtin_amdgcn_sched_barrier(0)
; template <class Epi, class Sched>
; __device__ __forceinline__ void gemm_phase(LAS unsigned char* lds, const Gemm g, const Sched& S, const Epi& E) {
;     ...
;             PG8_BAR; PG8_WAIT_L(0); PG8_MMA(1, 0, At, B0); PG8_BAR; PG8_SCHED;
;             PG8_STAGE(PG8_SB(0, 1), b2 + hstepB, voffB);
;             PG8_WAIT_V(6); PG8_BAR; PG8_MMA(1, 1, At, B1); PG8_BAR;
;             PG8_LDB(B0, 1, 0); PG8_SCHED; PG8_LDA(At, 1, 0); PG8_STAGE(PG8_SA(0, 1), a2 + hstepA, voffA);
;             PG8_WAIT_L(8); PG8_BAR; PG8_WAIT_L(0); PG8_MMA(0, 0, At, B0); PG8_BAR; PG8_SCHED;
;             PG8_LDB(B1, 1, 1); PG8_STAGE(PG8_SB(1, 0), b3, voffB);
;             PG8_BAR; PG8_WAIT_L(0); PG8_MMA(0, 1, At, B1); PG8_BAR;
	v_mfma_f32_16x16x32_bf16 v[64:67], v[132:135], v[148:151], 0
	v_mfma_f32_16x16x32_bf16 v[60:63], v[140:143], v[148:151], 0
	v_mfma_f32_16x16x32_bf16 v[52:55], v[132:135], v[156:159], 0
	v_mfma_f32_16x16x32_bf16 v[44:47], v[140:143], v[156:159], 0
	v_mfma_f32_16x16x32_bf16 v[36:39], v[132:135], v[164:167], 0
	v_mfma_f32_16x16x32_bf16 v[28:31], v[140:143], v[164:167], 0
	v_mfma_f32_16x16x32_bf16 v[20:23], v[132:135], v[172:175], 0
	v_mfma_f32_16x16x32_bf16 v[12:15], v[140:143], v[172:175], 0
	v_mfma_f32_16x16x32_bf16 v[64:67], v[136:139], v[152:155], v[64:67]
	v_mfma_f32_16x16x32_bf16 v[60:63], v[144:147], v[152:155], v[60:63]
	v_mfma_f32_16x16x32_bf16 v[52:55], v[136:139], v[160:163], v[52:55]
	v_mfma_f32_16x16x32_bf16 v[44:47], v[144:147], v[160:163], v[44:47]
	v_mfma_f32_16x16x32_bf16 v[36:39], v[136:139], v[168:171], v[36:39]
	v_mfma_f32_16x16x32_bf16 v[28:31], v[144:147], v[168:171], v[28:31]
	v_mfma_f32_16x16x32_bf16 v[20:23], v[136:139], v[176:179], v[20:23]
	v_mfma_f32_16x16x32_bf16 v[12:15], v[144:147], v[176:179], v[12:15]
	v_mfma_f32_16x16x32_bf16 v[56:59], v[180:183], v[148:151], 0
	v_mfma_f32_16x16x32_bf16 v[48:51], v[188:191], v[148:151], 0
	v_mfma_f32_16x16x32_bf16 v[40:43], v[180:183], v[156:159], 0
	v_mfma_f32_16x16x32_bf16 v[32:35], v[188:191], v[156:159], 0
	v_mfma_f32_16x16x32_bf16 v[24:27], v[180:183], v[164:167], 0
	v_mfma_f32_16x16x32_bf16 v[16:19], v[188:191], v[164:167], 0
	v_mfma_f32_16x16x32_bf16 v[8:11], v[180:183], v[172:175], 0
	v_mfma_f32_16x16x32_bf16 v[4:7], v[188:191], v[172:175], 0
	v_mfma_f32_16x16x32_bf16 v[56:59], v[184:187], v[152:155], v[56:59]
	v_mfma_f32_16x16x32_bf16 v[48:51], v[202:205], v[152:155], v[48:51]
	v_mfma_f32_16x16x32_bf16 v[40:43], v[184:187], v[160:163], v[40:43]
	v_mfma_f32_16x16x32_bf16 v[32:35], v[202:205], v[160:163], v[32:35]
	v_mfma_f32_16x16x32_bf16 v[24:27], v[184:187], v[168:171], v[24:27]
	v_mfma_f32_16x16x32_bf16 v[16:19], v[202:205], v[168:171], v[16:19]
	v_mfma_f32_16x16x32_bf16 v[8:11], v[184:187], v[176:179], v[8:11]
	v_mfma_f32_16x16x32_bf16 v[4:7], v[202:205], v[176:179], v[4:7]
	s_barrier
	s_setprio 0
	s_add_i32 s52, 0, 0x18000
	v_add_u32_e32 v144, s52, v1
	ds_read_b128 v[132:135], v144
	ds_read_b128 v[136:139], v144 offset:1024
	ds_read_b128 v[140:143], v144 offset:2048
	ds_read_b128 v[144:147], v144 offset:3072
	s_add_u32 s24, s24, 0x80000
	s_addc_u32 s25, s25, 0
	ds_read_b128 v[148:151], v224 offset:32768
	ds_read_b128 v[152:155], v224 offset:33792
	ds_read_b128 v[156:159], v224 offset:34816
	ds_read_b128 v[160:163], v224 offset:35840
	ds_read_b128 v[164:167], v224 offset:36864
	ds_read_b128 v[168:171], v224 offset:37888
	ds_read_b128 v[172:175], v224 offset:38912
	ds_read_b128 v[176:179], v224 offset:39936
	s_mov_b32 m0, s36
	s_nop 0
	global_load_lds_dwordx4 v196, s[24:25]
	s_mov_b32 m0, s37
	s_nop 0
	global_load_lds_dwordx4 v194, s[24:25]
	s_add_i32 s24, 0, 0x1c000
	v_add_u32_e32 v202, s24, v1
	ds_read_b128 v[180:183], v202
	ds_read_b128 v[184:187], v202 offset:1024
	ds_read_b128 v[188:191], v202 offset:2048
	ds_read_b128 v[202:205], v202 offset:3072
	s_waitcnt lgkmcnt(0)
	s_setprio 1
	s_barrier
	v_mfma_f32_16x16x32_bf16 v[128:131], v[132:135], v[148:151], v[128:131]
	v_mfma_f32_16x16x32_bf16 v[124:127], v[140:143], v[148:151], v[124:127]
	v_mfma_f32_16x16x32_bf16 v[112:115], v[132:135], v[156:159], v[112:115]
	v_mfma_f32_16x16x32_bf16 v[108:111], v[140:143], v[156:159], v[108:111]
	v_mfma_f32_16x16x32_bf16 v[100:103], v[132:135], v[164:167], v[100:103]
	v_mfma_f32_16x16x32_bf16 v[92:95], v[140:143], v[164:167], v[92:95]
	v_mfma_f32_16x16x32_bf16 v[84:87], v[132:135], v[172:175], v[84:87]
	v_mfma_f32_16x16x32_bf16 v[76:79], v[140:143], v[172:175], v[76:79]
	v_mfma_f32_16x16x32_bf16 v[128:131], v[136:139], v[152:155], v[128:131]
	v_mfma_f32_16x16x32_bf16 v[124:127], v[144:147], v[152:155], v[124:127]
	v_mfma_f32_16x16x32_bf16 v[112:115], v[136:139], v[160:163], v[112:115]
	v_mfma_f32_16x16x32_bf16 v[108:111], v[144:147], v[160:163], v[108:111]
	v_mfma_f32_16x16x32_bf16 v[100:103], v[136:139], v[168:171], v[100:103]
	v_mfma_f32_16x16x32_bf16 v[92:95], v[144:147], v[168:171], v[92:95]
	v_mfma_f32_16x16x32_bf16 v[84:87], v[136:139], v[176:179], v[84:87]
	v_mfma_f32_16x16x32_bf16 v[76:79], v[144:147], v[176:179], v[76:79]
	v_mfma_f32_16x16x32_bf16 v[120:123], v[180:183], v[148:151], v[120:123]
	v_mfma_f32_16x16x32_bf16 v[116:119], v[188:191], v[148:151], v[116:119]
	v_mfma_f32_16x16x32_bf16 v[104:107], v[180:183], v[156:159], v[104:107]
	v_mfma_f32_16x16x32_bf16 v[96:99], v[188:191], v[156:159], v[96:99]
	v_mfma_f32_16x16x32_bf16 v[88:91], v[180:183], v[164:167], v[88:91]
	v_mfma_f32_16x16x32_bf16 v[80:83], v[188:191], v[164:167], v[80:83]
	v_mfma_f32_16x16x32_bf16 v[72:75], v[180:183], v[172:175], v[72:75]
	v_mfma_f32_16x16x32_bf16 v[68:71], v[188:191], v[172:175], v[68:71]
	v_mfma_f32_16x16x32_bf16 v[120:123], v[184:187], v[152:155], v[120:123]
	v_mfma_f32_16x16x32_bf16 v[116:119], v[202:205], v[152:155], v[116:119]
	v_mfma_f32_16x16x32_bf16 v[104:107], v[184:187], v[160:163], v[104:107]
	v_mfma_f32_16x16x32_bf16 v[96:99], v[202:205], v[160:163], v[96:99]
	v_mfma_f32_16x16x32_bf16 v[88:91], v[184:187], v[168:171], v[88:91]
	v_mfma_f32_16x16x32_bf16 v[80:83], v[202:205], v[168:171], v[80:83]
	v_mfma_f32_16x16x32_bf16 v[72:75], v[184:187], v[176:179], v[72:75]
	v_mfma_f32_16x16x32_bf16 v[68:71], v[202:205], v[176:179], v[68:71]
	s_barrier
; #define PG8_STAGE(bufoff, gbase, voff) do { _Pragma("unroll") for (int _i = 0; _i < 2; ++_i) \
;         __builtin_amdgcn_global_load_lds((const unsigned*)((const char*)(gbase) + (voff)[_i]), (LAS unsigned*)(lds + (bufoff) + ldsw + _i * 8192), 16, 0, 0); } while (0)
; #define PG8_LDA(dst, b, h) do { _Pragma("unroll") for (int m = 0; m < 4; ++m) _Pragma("unroll") for (int k = 0; k < 2; ++k) dst[m][k] = *(const LAS bf16x8*)(lds + PG8_SA(b, h) + aoff + m * 2048 + k * 1024); } while (0)
; #define PG8_LDB(dst, b, h) do { _Pragma("unroll") for (int n = 0; n < 2; ++n) _Pragma("unroll") for (int k = 0; k < 2; ++k) dst[n][k] = *(const LAS bf16x8*)(lds + PG8_SB(b, h) + boff + n * 2048 + k * 1024); } while (0)
; #define PG8_MMA(ai, bj, At, Bt) do { __builtin_amdgcn_s_setprio(1); _Pragma("unroll") for (int m = 0; m < 4; ++m) _Pragma("unroll") for (int n = 0; n < 2; ++n) _Pragma("unroll") for (int k = 0; k < 2; ++k) \
;         acc[ai][bj][m][n] = __builtin_amdgcn_mfma_f32_16x16x32_bf16(Bt[n][k], At[m][k], acc[ai][bj][m][n], 0, 0, 0); __builtin_amdgcn_s_setprio(0); } while (0)
; #define PG8_WAIT_V(n) asm volatile("s_waitcnt vmcnt(" #n ")" ::: "memory")
; #define PG8_WAIT_L(n) asm volatile("s_waitcnt lgkmcnt(" #n ")" ::: "memory")
; #define PG8_BAR __builtin_amdgcn_s_barrier()
; #define PG8_SCHED __builtin_amdgcn_sched_barrier(0)
; template <class Epi, class Sched>
; __device__ __forceinline__ void gemm_phase(LAS unsigned char* lds, const Gemm g, const Sched& S, const Epi& E) {
;     ...
;             PG8_LDB(B1, 1, 1); PG8_STAGE(PG8_SB(1, 0), b3, voffB);
;             PG8_BAR; PG8_WAIT_L(0); PG8_MMA(0, 1, At, B1); PG8_BAR;
;             PG8_LDA(At, 1, 1); PG8_STAGE(PG8_SA(1, 0), a3, voffA);
;             PG8_BAR; PG8_WAIT_L(0); PG8_MMA(1, 0, At, B0); PG8_BAR; PG8_SCHED;
;             PG8_STAGE(PG8_SB(1, 1), b3 + hstepB, voffB);
;             PG8_WAIT_V(6); PG8_BAR; PG8_MMA(1, 1, At, B1); PG8_BAR;
	s_setprio 0
	ds_read_b128 v[148:151], v224 offset:49152
	ds_read_b128 v[152:155], v224 offset:50176
	ds_read_b128 v[156:159], v224 offset:51200
	ds_read_b128 v[160:163], v224 offset:52224
	ds_read_b128 v[164:167], v224 offset:53248
	ds_read_b128 v[168:171], v224 offset:54272
	ds_read_b128 v[172:175], v224 offset:55296
	ds_read_b128 v[176:179], v224 offset:56320
	s_add_i32 s25, s52, s30
	v_lshl_add_u64 v[206:207], v[206:207], 0, s[8:9]
	s_mov_b32 m0, s25
	s_nop 0
	global_load_lds_dwordx4 v[206:207], off
	v_lshl_add_u64 v[206:207], v[208:209], 0, s[8:9]
	s_add_i32 m0, s25, 0x2000
	s_nop 0
	global_load_lds_dwordx4 v[206:207], off
	s_mov_b32 m0, s40
	v_lshl_add_u64 v[206:207], v[210:211], 0, s[8:9]
	global_load_lds_dwordx4 v[206:207], off
	v_lshl_add_u64 v[206:207], v[212:213], 0, s[8:9]
	s_mov_b32 m0, s41
	s_nop 0
	global_load_lds_dwordx4 v[206:207], off
	s_add_u32 s20, s20, 0x80080
	s_addc_u32 s21, s21, 0
	s_add_i32 s24, s24, s30
	s_mov_b32 m0, s24
	s_nop 0
	global_load_lds_dwordx4 v2, s[20:21]
	s_add_i32 m0, s24, 0x2000
	s_nop 0
	global_load_lds_dwordx4 v192, s[20:21]
	s_add_i32 s51, s51, 2
	s_add_u32 s6, s6, 0x100
	s_addc_u32 s7, s7, 0
	s_add_u32 s49, s49, 0x100
	s_addc_u32 s50, s50, 0
	s_cmp_gt_u32 s51, 29
	s_waitcnt lgkmcnt(0)
	s_waitcnt vmcnt(6)
	s_setprio 1
	s_barrier
	v_mfma_f32_16x16x32_bf16 v[64:67], v[132:135], v[148:151], v[64:67]
	v_mfma_f32_16x16x32_bf16 v[60:63], v[140:143], v[148:151], v[60:63]
	v_mfma_f32_16x16x32_bf16 v[52:55], v[132:135], v[156:159], v[52:55]
	v_mfma_f32_16x16x32_bf16 v[44:47], v[140:143], v[156:159], v[44:47]
	v_mfma_f32_16x16x32_bf16 v[36:39], v[132:135], v[164:167], v[36:39]
	v_mfma_f32_16x16x32_bf16 v[28:31], v[140:143], v[164:167], v[28:31]
	v_mfma_f32_16x16x32_bf16 v[20:23], v[132:135], v[172:175], v[20:23]
	v_mfma_f32_16x16x32_bf16 v[12:15], v[140:143], v[172:175], v[12:15]
	v_mfma_f32_16x16x32_bf16 v[64:67], v[136:139], v[152:155], v[64:67]
	v_mfma_f32_16x16x32_bf16 v[60:63], v[144:147], v[152:155], v[60:63]
	v_mfma_f32_16x16x32_bf16 v[52:55], v[136:139], v[160:163], v[52:55]
	v_mfma_f32_16x16x32_bf16 v[44:47], v[144:147], v[160:163], v[44:47]
	v_mfma_f32_16x16x32_bf16 v[36:39], v[136:139], v[168:171], v[36:39]
	v_mfma_f32_16x16x32_bf16 v[28:31], v[144:147], v[168:171], v[28:31]
	v_mfma_f32_16x16x32_bf16 v[20:23], v[136:139], v[176:179], v[20:23]
	v_mfma_f32_16x16x32_bf16 v[12:15], v[144:147], v[176:179], v[12:15]
	v_mfma_f32_16x16x32_bf16 v[56:59], v[180:183], v[148:151], v[56:59]
	v_mfma_f32_16x16x32_bf16 v[48:51], v[188:191], v[148:151], v[48:51]
	v_mfma_f32_16x16x32_bf16 v[40:43], v[180:183], v[156:159], v[40:43]
	v_mfma_f32_16x16x32_bf16 v[32:35], v[188:191], v[156:159], v[32:35]
	v_mfma_f32_16x16x32_bf16 v[24:27], v[180:183], v[164:167], v[24:27]
	v_mfma_f32_16x16x32_bf16 v[16:19], v[188:191], v[164:167], v[16:19]
	v_mfma_f32_16x16x32_bf16 v[8:11], v[180:183], v[172:175], v[8:11]
	v_mfma_f32_16x16x32_bf16 v[4:7], v[188:191], v[172:175], v[4:7]
	v_mfma_f32_16x16x32_bf16 v[56:59], v[184:187], v[152:155], v[56:59]
	v_mfma_f32_16x16x32_bf16 v[48:51], v[202:205], v[152:155], v[48:51]
	v_mfma_f32_16x16x32_bf16 v[40:43], v[184:187], v[160:163], v[40:43]
	v_mfma_f32_16x16x32_bf16 v[32:35], v[202:205], v[160:163], v[32:35]
	v_mfma_f32_16x16x32_bf16 v[24:27], v[184:187], v[168:171], v[24:27]
	v_mfma_f32_16x16x32_bf16 v[16:19], v[202:205], v[168:171], v[16:19]
	v_mfma_f32_16x16x32_bf16 v[8:11], v[184:187], v[176:179], v[8:11]
	v_mfma_f32_16x16x32_bf16 v[4:7], v[202:205], v[176:179], v[4:7]
	s_barrier
	s_setprio 0

; #define PG8_STAGE(bufoff, gbase, voff) do { _Pragma("unroll") for (int _i = 0; _i < 2; ++_i) \
;         __builtin_amdgcn_global_load_lds((const unsigned*)((const char*)(gbase) + (voff)[_i]), (LAS unsigned*)(lds + (bufoff) + ldsw + _i * 8192), 16, 0, 0); } while (0)
; #define PG8_LDA(dst, b, h) do { _Pragma("unroll") for (int m = 0; m < 4; ++m) _Pragma("unroll") for (int k = 0; k < 2; ++k) dst[m][k] = *(const LAS bf16x8*)(lds + PG8_SA(b, h) + aoff + m * 2048 + k * 1024); } while (0)
; #define PG8_LDB(dst, b, h) do { _Pragma("unroll") for (int n = 0; n < 2; ++n) _Pragma("unroll") for (int k = 0; k < 2; ++k) dst[n][k] = *(const LAS bf16x8*)(lds + PG8_SB(b, h) + boff + n * 2048 + k * 1024); } while (0)
; #define PG8_WAIT_V(n) asm volatile("s_waitcnt vmcnt(" #n ")" ::: "memory")
; #define PG8_WAIT_L(n) asm volatile("s_waitcnt lgkmcnt(" #n ")" ::: "memory")
; #define PG8_BAR __builtin_amdgcn_s_barrier()
; #define PG8_SCHED __builtin_amdgcn_sched_barrier(0)
; template <class Epi, class Sched>
; __device__ __forceinline__ void gemm_phase(LAS unsigned char* lds, const Gemm g, const Sched& S, const Epi& E) {
;     ...
;         const bool has_next = S.next(ui + 1, nxt);
;         const char* nA = has_next ? (const char*)g.A + (size_t)nxt.pm * tstepA : cA; const char* nB = has_next ? (const char*)g.Bt + (size_t)nxt.pn * tstepB : cB;
;         for (int t = 0; t < nt; t += 2) {
;             const bool last = (t == nt - 2);
;             const char* a1 = cA + (size_t)(t + 1) * kstep;
;             const char* a2 = last ? nA : cA + (size_t)(t + 2) * kstep; const char* b2 = last ? nB : cB + (size_t)(t + 2) * kstep;
;             const char* a3 = a2 + kstep; const char* b3 = b2 + kstep;
;             if (last && has_next) S.a_ready(nxt);
;             PG8_LDB(B0, 0, 0); PG8_SCHED; PG8_LDA(At, 0, 0); PG8_STAGE(PG8_SA(1, 1), a1 + hstepA, voffA);
;             PG8_WAIT_L(8); PG8_BAR; PG8_WAIT_L(0); PG8_MMA(0, 0, At, B0); PG8_BAR; PG8_SCHED;
;             PG8_LDB(B1, 0, 1); PG8_STAGE(PG8_SB(0, 0), b2, voffB);
;             PG8_BAR; PG8_WAIT_L(0); PG8_MMA(0, 1, At, B1); PG8_BAR;
;             PG8_LDA(At, 0, 1); PG8_STAGE(PG8_SA(0, 0), a2, voffA);
;             PG8_BAR; PG8_WAIT_L(0); PG8_MMA(1, 0, At, B0); PG8_BAR; PG8_SCHED;
;             PG8_STAGE(PG8_SB(0, 1), b2 + hstepB, voffB);
;             PG8_WAIT_V(6); PG8_BAR; PG8_MMA(1, 1, At, B1); PG8_BAR;
.LBB0_1395:
	v_mov_b64_e32 v[4:5], 0x400
	s_ashr_i32 s15, s14, 31
	v_cmp_lt_i64_e32 vcc, s[4:5], v[4:5]
	s_lshl_b64 s[4:5], s[14:15], 20
	v_readlane_b32 s48, v252, 0
	v_readlane_b32 s49, v252, 1
	s_add_u32 s4, s48, s4
	s_addc_u32 s5, s49, s5
	s_and_b64 s[18:19], vcc, exec
	s_cselect_b32 s15, s5, s7
	s_cselect_b32 s47, s4, s6
	s_ashr_i32 s1, s0, 31
	s_lshl_b64 s[18:19], s[0:1], 20
	s_add_u32 s18, s28, s18
	s_addc_u32 s19, s29, s19
	s_and_b64 s[24:25], vcc, exec
	s_cselect_b32 s1, s19, s21
	s_cselect_b32 s48, s18, s20
	s_add_u32 s6, s6, 0x80080
	s_addc_u32 s7, s7, 0
	v_readlane_b32 s50, v252, 2
	v_readlane_b32 s51, v252, 3
	s_add_u32 s49, s20, 0x100
	s_addc_u32 s50, s21, 0
	s_mov_b32 s51, -2
	s_setprio 0
	s_add_u32 s20, s6, 0xfff80080
	s_addc_u32 s21, s7, -1
	s_add_i32 s52, 0, 0x10000
	v_add_u32_e32 v144, s52, v1
	ds_read_b128 v[132:135], v144
	ds_read_b128 v[136:139], v144 offset:1024
	ds_read_b128 v[140:143], v144 offset:2048
	ds_read_b128 v[144:147], v144 offset:3072
	s_cmp_eq_u32 s51, 28
	s_cselect_b32 s25, s15, s21
	s_cselect_b32 s24, s47, s20
	s_cselect_b32 s21, s1, s50
	s_cselect_b32 s20, s48, s49
	ds_read_b128 v[148:151], v224
	ds_read_b128 v[152:155], v224 offset:1024
	ds_read_b128 v[156:159], v224 offset:2048
	ds_read_b128 v[160:163], v224 offset:3072
	ds_read_b128 v[164:167], v224 offset:4096
	ds_read_b128 v[168:171], v224 offset:5120
	ds_read_b128 v[172:175], v224 offset:6144
	ds_read_b128 v[176:179], v224 offset:7168
	s_add_i32 s54, 0, 0x14000
	v_add_u32_e32 v202, s54, v1
	ds_read_b128 v[180:183], v202
	ds_read_b128 v[184:187], v202 offset:1024
	ds_read_b128 v[188:191], v202 offset:2048
	ds_read_b128 v[202:205], v202 offset:3072
	s_add_i32 m0, s31, 0xc000
	s_nop 0
	global_load_lds_dwordx4 v198, s[6:7]
	s_add_i32 m0, s31, 0xe000
	s_nop 0
	global_load_lds_dwordx4 v200, s[6:7]
	s_waitcnt lgkmcnt(0)
	s_setprio 1
	s_barrier
	v_mfma_f32_16x16x32_bf16 v[128:131], v[132:135], v[148:151], 0
	v_mfma_f32_16x16x32_bf16 v[124:127], v[140:143], v[148:151], 0
	v_mfma_f32_16x16x32_bf16 v[112:115], v[132:135], v[156:159], 0
	v_mfma_f32_16x16x32_bf16 v[108:111], v[140:143], v[156:159], 0
	v_mfma_f32_16x16x32_bf16 v[100:103], v[132:135], v[164:167], 0
	v_mfma_f32_16x16x32_bf16 v[92:95], v[140:143], v[164:167], 0
	v_mfma_f32_16x16x32_bf16 v[84:87], v[132:135], v[172:175], 0
	v_mfma_f32_16x16x32_bf16 v[76:79], v[140:143], v[172:175], 0
	v_mfma_f32_16x16x32_bf16 v[128:131], v[136:139], v[152:155], v[128:131]
	v_mfma_f32_16x16x32_bf16 v[124:127], v[144:147], v[152:155], v[124:127]
	v_mfma_f32_16x16x32_bf16 v[112:115], v[136:139], v[160:163], v[112:115]
	v_mfma_f32_16x16x32_bf16 v[108:111], v[144:147], v[160:163], v[108:111]
	v_mfma_f32_16x16x32_bf16 v[100:103], v[136:139], v[168:171], v[100:103]
	v_mfma_f32_16x16x32_bf16 v[92:95], v[144:147], v[168:171], v[92:95]
	v_mfma_f32_16x16x32_bf16 v[84:87], v[136:139], v[176:179], v[84:87]
	v_mfma_f32_16x16x32_bf16 v[76:79], v[144:147], v[176:179], v[76:79]
	v_mfma_f32_16x16x32_bf16 v[120:123], v[180:183], v[148:151], 0
	v_mfma_f32_16x16x32_bf16 v[116:119], v[188:191], v[148:151], 0
	v_mfma_f32_16x16x32_bf16 v[104:107], v[180:183], v[156:159], 0
	v_mfma_f32_16x16x32_bf16 v[96:99], v[188:191], v[156:159], 0
	v_mfma_f32_16x16x32_bf16 v[88:91], v[180:183], v[164:167], 0
	v_mfma_f32_16x16x32_bf16 v[80:83], v[188:191], v[164:167], 0
	v_mfma_f32_16x16x32_bf16 v[72:75], v[180:183], v[172:175], 0
	v_mfma_f32_16x16x32_bf16 v[68:71], v[188:191], v[172:175], 0
	v_mfma_f32_16x16x32_bf16 v[120:123], v[184:187], v[152:155], v[120:123]
	v_mfma_f32_16x16x32_bf16 v[116:119], v[202:205], v[152:155], v[116:119]
	v_mfma_f32_16x16x32_bf16 v[104:107], v[184:187], v[160:163], v[104:107]
	v_mfma_f32_16x16x32_bf16 v[96:99], v[202:205], v[160:163], v[96:99]
	v_mfma_f32_16x16x32_bf16 v[88:91], v[184:187], v[168:171], v[88:91]
	v_mfma_f32_16x16x32_bf16 v[80:83], v[202:205], v[168:171], v[80:83]
	v_mfma_f32_16x16x32_bf16 v[72:75], v[184:187], v[176:179], v[72:75]
	v_mfma_f32_16x16x32_bf16 v[68:71], v[202:205], v[176:179], v[68:71]
	s_barrier
	s_setprio 0
	ds_read_b128 v[148:151], v224 offset:16384
	ds_read_b128 v[152:155], v224 offset:17408
	ds_read_b128 v[156:159], v224 offset:18432
	ds_read_b128 v[160:163], v224 offset:19456
	ds_read_b128 v[164:167], v224 offset:20480
	ds_read_b128 v[168:171], v224 offset:21504
	ds_read_b128 v[172:175], v224 offset:22528
	ds_read_b128 v[176:179], v224 offset:23552
	s_add_i32 s52, s52, s30
	v_lshl_add_u64 v[206:207], s[20:21], 0, v[2:3]
	s_mov_b32 m0, s52
	s_nop 0
	global_load_lds_dwordx4 v[206:207], off
	v_lshl_add_u64 v[208:209], s[20:21], 0, v[192:193]
	s_add_i32 m0, s52, 0x2000
	s_nop 0
	global_load_lds_dwordx4 v[208:209], off
	s_mov_b32 m0, s31
	v_lshl_add_u64 v[210:211], s[24:25], 0, v[196:197]
	global_load_lds_dwordx4 v[210:211], off
	v_lshl_add_u64 v[212:213], s[24:25], 0, v[194:195]
	s_mov_b32 m0, s35
	s_nop 0
	global_load_lds_dwordx4 v[212:213], off
	s_add_u32 s52, s20, 0x80000
	s_addc_u32 s53, s21, 0
	s_add_i32 s54, s54, s30
	s_mov_b32 m0, s54
	s_nop 0
	global_load_lds_dwordx4 v2, s[52:53]
	s_add_i32 m0, s54, 0x2000
	s_nop 0
	global_load_lds_dwordx4 v192, s[52:53]
	s_waitcnt lgkmcnt(0)
	s_waitcnt vmcnt(6)
	s_setprio 1
	s_barrier
; #define PG8_STAGE(bufoff, gbase, voff) do { _Pragma("unroll") for (int _i = 0; _i < 2; ++_i) \
;         __builtin_amdgcn_global_load_lds((const unsigned*)((const char*)(gbase) + (voff)[_i]), (LAS unsigned*)(lds + (bufoff) + ldsw + _i * 8192), 16, 0, 0); } while (0)
; #define PG8_LDA(dst, b, h) do { _Pragma("unroll") for (int m = 0; m < 4; ++m) _Pragma("unroll") for (int k = 0; k < 2; ++k) dst[m][k] = *(const LAS bf16x8*)(lds + PG8_SA(b, h) + aoff + m * 2048 + k * 1024); } while (0)
; #define PG8_LDB(dst, b, h) do { _Pragma("unroll") for (int n = 0; n < 2; ++n) _Pragma("unroll") for (int k = 0; k < 2; ++k) dst[n][k] = *(const LAS bf16x8*)(lds + PG8_SB(b, h) + boff + n * 2048 + k * 1024); } while (0)
; #define PG8_MMA(ai, bj, At, Bt) do { __builtin_amdgcn_s_setprio(1); _Pragma("unroll") for (int m = 0; m < 4; ++m) _Pragma("unroll") for (int n = 0; n < 2; ++n) _Pragma("unroll") for (int k = 0; k < 2; ++k) \
;         acc[ai][bj][m][n] = __builtin_amdgcn_mfma_f32_16x16x32_bf16(Bt[n][k], At[m][k], acc[ai][bj][m][n], 0, 0, 0); __builtin_amdgcn_s_setprio(0); } while (0)
; #define PG8_WAIT_V(n) asm volatile("s_waitcnt vmcnt(" #n ")" ::: "memory")
; #define PG8_WAIT_L(n) asm volatile("s_waitcnt lgkmcnt(" #n ")" ::: "memory")
; #define PG8_BAR __builtin_amdgcn_s_barrier()
; #define PG8_SCHED __builtin_amdgcn_sched_barrier(0)
; template <class Epi, class Sched>
; __device__ __forceinline__ void gemm_phase(LAS unsigned char* lds, const Gemm g, const Sched& S, const Epi& E) {
;     ...
;             PG8_BAR; PG8_WAIT_L(0); PG8_MMA(1, 0, At, B0); PG8_BAR; PG8_SCHED;
;             PG8_STAGE(PG8_SB(0, 1), b2 + hstepB, voffB);
;             PG8_WAIT_V(6); PG8_BAR; PG8_MMA(1, 1, At, B1); PG8_BAR;
;             PG8_LDB(B0, 1, 0); PG8_SCHED; PG8_LDA(At, 1, 0); PG8_STAGE(PG8_SA(0, 1), a2 + hstepA, voffA);
;             PG8_WAIT_L(8); PG8_BAR; PG8_WAIT_L(0); PG8_MMA(0, 0, At, B0); PG8_BAR; PG8_SCHED;
;             PG8_LDB(B1, 1, 1); PG8_STAGE(PG8_SB(1, 0), b3, voffB);
;             PG8_BAR; PG8_WAIT_L(0); PG8_MMA(0, 1, At, B1); PG8_BAR;
	v_mfma_f32_16x16x32_bf16 v[64:67], v[132:135], v[148:151], 0
	v_mfma_f32_16x16x32_bf16 v[60:63], v[140:143], v[148:151], 0
	v_mfma_f32_16x16x32_bf16 v[52:55], v[132:135], v[156:159], 0
	v_mfma_f32_16x16x32_bf16 v[44:47], v[140:143], v[156:159], 0
	v_mfma_f32_16x16x32_bf16 v[36:39], v[132:135], v[164:167], 0
	v_mfma_f32_16x16x32_bf16 v[28:31], v[140:143], v[164:167], 0
	v_mfma_f32_16x16x32_bf16 v[20:23], v[132:135], v[172:175], 0
	v_mfma_f32_16x16x32_bf16 v[12:15], v[140:143], v[172:175], 0
	v_mfma_f32_16x16x32_bf16 v[64:67], v[136:139], v[152:155], v[64:67]
	v_mfma_f32_16x16x32_bf16 v[60:63], v[144:147], v[152:155], v[60:63]
	v_mfma_f32_16x16x32_bf16 v[52:55], v[136:139], v[160:163], v[52:55]
	v_mfma_f32_16x16x32_bf16 v[44:47], v[144:147], v[160:163], v[44:47]
	v_mfma_f32_16x16x32_bf16 v[36:39], v[136:139], v[168:171], v[36:39]
	v_mfma_f32_16x16x32_bf16 v[28:31], v[144:147], v[168:171], v[28:31]
	v_mfma_f32_16x16x32_bf16 v[20:23], v[136:139], v[176:179], v[20:23]
	v_mfma_f32_16x16x32_bf16 v[12:15], v[144:147], v[176:179], v[12:15]
	v_mfma_f32_16x16x32_bf16 v[56:59], v[180:183], v[148:151], 0
	v_mfma_f32_16x16x32_bf16 v[48:51], v[188:191], v[148:151], 0
	v_mfma_f32_16x16x32_bf16 v[40:43], v[180:183], v[156:159], 0
	v_mfma_f32_16x16x32_bf16 v[32:35], v[188:191], v[156:159], 0
	v_mfma_f32_16x16x32_bf16 v[24:27], v[180:183], v[164:167], 0
	v_mfma_f32_16x16x32_bf16 v[16:19], v[188:191], v[164:167], 0
	v_mfma_f32_16x16x32_bf16 v[8:11], v[180:183], v[172:175], 0
	v_mfma_f32_16x16x32_bf16 v[4:7], v[188:191], v[172:175], 0
	v_mfma_f32_16x16x32_bf16 v[56:59], v[184:187], v[152:155], v[56:59]
	v_mfma_f32_16x16x32_bf16 v[48:51], v[202:205], v[152:155], v[48:51]
	v_mfma_f32_16x16x32_bf16 v[40:43], v[184:187], v[160:163], v[40:43]
	v_mfma_f32_16x16x32_bf16 v[32:35], v[202:205], v[160:163], v[32:35]
	v_mfma_f32_16x16x32_bf16 v[24:27], v[184:187], v[168:171], v[24:27]
	v_mfma_f32_16x16x32_bf16 v[16:19], v[202:205], v[168:171], v[16:19]
	v_mfma_f32_16x16x32_bf16 v[8:11], v[184:187], v[176:179], v[8:11]
	v_mfma_f32_16x16x32_bf16 v[4:7], v[202:205], v[176:179], v[4:7]
	s_barrier
	s_setprio 0
	s_add_i32 s52, 0, 0x18000
	v_add_u32_e32 v144, s52, v1
	ds_read_b128 v[132:135], v144
	ds_read_b128 v[136:139], v144 offset:1024
	ds_read_b128 v[140:143], v144 offset:2048
	ds_read_b128 v[144:147], v144 offset:3072
	s_add_u32 s24, s24, 0x80000
	s_addc_u32 s25, s25, 0
	ds_read_b128 v[148:151], v224 offset:32768
	ds_read_b128 v[152:155], v224 offset:33792
	ds_read_b128 v[156:159], v224 offset:34816
	ds_read_b128 v[160:163], v224 offset:35840
	ds_read_b128 v[164:167], v224 offset:36864
	ds_read_b128 v[168:171], v224 offset:37888
	ds_read_b128 v[172:175], v224 offset:38912
	ds_read_b128 v[176:179], v224 offset:39936
	s_mov_b32 m0, s36
	s_nop 0
	global_load_lds_dwordx4 v196, s[24:25]
	s_mov_b32 m0, s37
	s_nop 0
	global_load_lds_dwordx4 v194, s[24:25]
	s_add_i32 s24, 0, 0x1c000
	v_add_u32_e32 v202, s24, v1
	ds_read_b128 v[180:183], v202
	ds_read_b128 v[184:187], v202 offset:1024
	ds_read_b128 v[188:191], v202 offset:2048
	ds_read_b128 v[202:205], v202 offset:3072
	s_waitcnt lgkmcnt(0)
	s_setprio 1
	s_barrier
	v_mfma_f32_16x16x32_bf16 v[128:131], v[132:135], v[148:151], v[128:131]
	v_mfma_f32_16x16x32_bf16 v[124:127], v[140:143], v[148:151], v[124:127]
	v_mfma_f32_16x16x32_bf16 v[112:115], v[132:135], v[156:159], v[112:115]
	v_mfma_f32_16x16x32_bf16 v[108:111], v[140:143], v[156:159], v[108:111]
	v_mfma_f32_16x16x32_bf16 v[100:103], v[132:135], v[164:167], v[100:103]
	v_mfma_f32_16x16x32_bf16 v[92:95], v[140:143], v[164:167], v[92:95]
	v_mfma_f32_16x16x32_bf16 v[84:87], v[132:135], v[172:175], v[84:87]
	v_mfma_f32_16x16x32_bf16 v[76:79], v[140:143], v[172:175], v[76:79]
	v_mfma_f32_16x16x32_bf16 v[128:131], v[136:139], v[152:155], v[128:131]
	v_mfma_f32_16x16x32_bf16 v[124:127], v[144:147], v[152:155], v[124:127]
	v_mfma_f32_16x16x32_bf16 v[112:115], v[136:139], v[160:163], v[112:115]
	v_mfma_f32_16x16x32_bf16 v[108:111], v[144:147], v[160:163], v[108:111]
	v_mfma_f32_16x16x32_bf16 v[100:103], v[136:139], v[168:171], v[100:103]
	v_mfma_f32_16x16x32_bf16 v[92:95], v[144:147], v[168:171], v[92:95]
	v_mfma_f32_16x16x32_bf16 v[84:87], v[136:139], v[176:179], v[84:87]
	v_mfma_f32_16x16x32_bf16 v[76:79], v[144:147], v[176:179], v[76:79]
	v_mfma_f32_16x16x32_bf16 v[120:123], v[180:183], v[148:151], v[120:123]
	v_mfma_f32_16x16x32_bf16 v[116:119], v[188:191], v[148:151], v[116:119]
	v_mfma_f32_16x16x32_bf16 v[104:107], v[180:183], v[156:159], v[104:107]
	v_mfma_f32_16x16x32_bf16 v[96:99], v[188:191], v[156:159], v[96:99]
	v_mfma_f32_16x16x32_bf16 v[88:91], v[180:183], v[164:167], v[88:91]
	v_mfma_f32_16x16x32_bf16 v[80:83], v[188:191], v[164:167], v[80:83]
	v_mfma_f32_16x16x32_bf16 v[72:75], v[180:183], v[172:175], v[72:75]
	v_mfma_f32_16x16x32_bf16 v[68:71], v[188:191], v[172:175], v[68:71]
	v_mfma_f32_16x16x32_bf16 v[120:123], v[184:187], v[152:155], v[120:123]
	v_mfma_f32_16x16x32_bf16 v[116:119], v[202:205], v[152:155], v[116:119]
	v_mfma_f32_16x16x32_bf16 v[104:107], v[184:187], v[160:163], v[104:107]
	v_mfma_f32_16x16x32_bf16 v[96:99], v[202:205], v[160:163], v[96:99]
	v_mfma_f32_16x16x32_bf16 v[88:91], v[184:187], v[168:171], v[88:91]
	v_mfma_f32_16x16x32_bf16 v[80:83], v[202:205], v[168:171], v[80:83]
	v_mfma_f32_16x16x32_bf16 v[72:75], v[184:187], v[176:179], v[72:75]
	v_mfma_f32_16x16x32_bf16 v[68:71], v[202:205], v[176:179], v[68:71]
	s_barrier
; #define PG8_STAGE(bufoff, gbase, voff) do { _Pragma("unroll") for (int _i = 0; _i < 2; ++_i) \
;         __builtin_amdgcn_global_load_lds((const unsigned*)((const char*)(gbase) + (voff)[_i]), (LAS unsigned*)(lds + (bufoff) + ldsw + _i * 8192), 16, 0, 0); } while (0)
; #define PG8_LDA(dst, b, h) do { _Pragma("unroll") for (int m = 0; m < 4; ++m) _Pragma("unroll") for (int k = 0; k < 2; ++k) dst[m][k] = *(const LAS bf16x8*)(lds + PG8_SA(b, h) + aoff + m * 2048 + k * 1024); } while (0)
; #define PG8_LDB(dst, b, h) do { _Pragma("unroll") for (int n = 0; n < 2; ++n) _Pragma("unroll") for (int k = 0; k < 2; ++k) dst[n][k] = *(const LAS bf16x8*)(lds + PG8_SB(b, h) + boff + n * 2048 + k * 1024); } while (0)
; #define PG8_MMA(ai, bj, At, Bt) do { __builtin_amdgcn_s_setprio(1); _Pragma("unroll") for (int m = 0; m < 4; ++m) _Pragma("unroll") for (int n = 0; n < 2; ++n) _Pragma("unroll") for (int k = 0; k < 2; ++k) \
;         acc[ai][bj][m][n] = __builtin_amdgcn_mfma_f32_16x16x32_bf16(Bt[n][k], At[m][k], acc[ai][bj][m][n], 0, 0, 0); __builtin_amdgcn_s_setprio(0); } while (0)
; #define PG8_WAIT_V(n) asm volatile("s_waitcnt vmcnt(" #n ")" ::: "memory")
; #define PG8_WAIT_L(n) asm volatile("s_waitcnt lgkmcnt(" #n ")" ::: "memory")
; #define PG8_BAR __builtin_amdgcn_s_barrier()
; #define PG8_SCHED __builtin_amdgcn_sched_barrier(0)
; template <class Epi, class Sched>
; __device__ __forceinline__ void gemm_phase(LAS unsigned char* lds, const Gemm g, const Sched& S, const Epi& E) {
;     ...
;             PG8_LDB(B1, 1, 1); PG8_STAGE(PG8_SB(1, 0), b3, voffB);
;             PG8_BAR; PG8_WAIT_L(0); PG8_MMA(0, 1, At, B1); PG8_BAR;
;             PG8_LDA(At, 1, 1); PG8_STAGE(PG8_SA(1, 0), a3, voffA);
;             PG8_BAR; PG8_WAIT_L(0); PG8_MMA(1, 0, At, B0); PG8_BAR; PG8_SCHED;
;             PG8_STAGE(PG8_SB(1, 1), b3 + hstepB, voffB);
;             PG8_WAIT_V(6); PG8_BAR; PG8_MMA(1, 1, At, B1); PG8_BAR;
	s_setprio 0
	ds_read_b128 v[148:151], v224 offset:49152
	ds_read_b128 v[152:155], v224 offset:50176
	ds_read_b128 v[156:159], v224 offset:51200
	ds_read_b128 v[160:163], v224 offset:52224
	ds_read_b128 v[164:167], v224 offset:53248
	ds_read_b128 v[168:171], v224 offset:54272
	ds_read_b128 v[172:175], v224 offset:55296
	ds_read_b128 v[176:179], v224 offset:56320
	s_add_i32 s25, s52, s30
	v_lshl_add_u64 v[206:207], v[206:207], 0, s[8:9]
	s_mov_b32 m0, s25
	s_nop 0
	global_load_lds_dwordx4 v[206:207], off
	v_lshl_add_u64 v[206:207], v[208:209], 0, s[8:9]
	s_add_i32 m0, s25, 0x2000
	s_nop 0
	global_load_lds_dwordx4 v[206:207], off
	s_mov_b32 m0, s42
	v_lshl_add_u64 v[206:207], v[210:211], 0, s[8:9]
	global_load_lds_dwordx4 v[206:207], off
	v_lshl_add_u64 v[206:207], v[212:213], 0, s[8:9]
	s_mov_b32 m0, s43
	s_nop 0
	global_load_lds_dwordx4 v[206:207], off
	s_add_u32 s20, s20, 0x80080
	s_addc_u32 s21, s21, 0
	s_add_i32 s24, s24, s30
	s_mov_b32 m0, s24
	s_nop 0
	global_load_lds_dwordx4 v2, s[20:21]
	s_add_i32 m0, s24, 0x2000
	s_nop 0
	global_load_lds_dwordx4 v192, s[20:21]
	s_add_i32 s51, s51, 2
	s_add_u32 s6, s6, 0x100
	s_addc_u32 s7, s7, 0
	s_add_u32 s49, s49, 0x100
	s_addc_u32 s50, s50, 0
	s_cmp_gt_u32 s51, 29
	s_waitcnt lgkmcnt(0)
	s_waitcnt vmcnt(6)
	s_setprio 1
	s_barrier
	v_mfma_f32_16x16x32_bf16 v[64:67], v[132:135], v[148:151], v[64:67]
	v_mfma_f32_16x16x32_bf16 v[60:63], v[140:143], v[148:151], v[60:63]
	v_mfma_f32_16x16x32_bf16 v[52:55], v[132:135], v[156:159], v[52:55]
	v_mfma_f32_16x16x32_bf16 v[44:47], v[140:143], v[156:159], v[44:47]
	v_mfma_f32_16x16x32_bf16 v[36:39], v[132:135], v[164:167], v[36:39]
	v_mfma_f32_16x16x32_bf16 v[28:31], v[140:143], v[164:167], v[28:31]
	v_mfma_f32_16x16x32_bf16 v[20:23], v[132:135], v[172:175], v[20:23]
	v_mfma_f32_16x16x32_bf16 v[12:15], v[140:143], v[172:175], v[12:15]
	v_mfma_f32_16x16x32_bf16 v[64:67], v[136:139], v[152:155], v[64:67]
	v_mfma_f32_16x16x32_bf16 v[60:63], v[144:147], v[152:155], v[60:63]
	v_mfma_f32_16x16x32_bf16 v[52:55], v[136:139], v[160:163], v[52:55]
	v_mfma_f32_16x16x32_bf16 v[44:47], v[144:147], v[160:163], v[44:47]
	v_mfma_f32_16x16x32_bf16 v[36:39], v[136:139], v[168:171], v[36:39]
	v_mfma_f32_16x16x32_bf16 v[28:31], v[144:147], v[168:171], v[28:31]
	v_mfma_f32_16x16x32_bf16 v[20:23], v[136:139], v[176:179], v[20:23]
	v_mfma_f32_16x16x32_bf16 v[12:15], v[144:147], v[176:179], v[12:15]
	v_mfma_f32_16x16x32_bf16 v[56:59], v[180:183], v[148:151], v[56:59]
	v_mfma_f32_16x16x32_bf16 v[48:51], v[188:191], v[148:151], v[48:51]
	v_mfma_f32_16x16x32_bf16 v[40:43], v[180:183], v[156:159], v[40:43]
	v_mfma_f32_16x16x32_bf16 v[32:35], v[188:191], v[156:159], v[32:35]
	v_mfma_f32_16x16x32_bf16 v[24:27], v[180:183], v[164:167], v[24:27]
	v_mfma_f32_16x16x32_bf16 v[16:19], v[188:191], v[164:167], v[16:19]
	v_mfma_f32_16x16x32_bf16 v[8:11], v[180:183], v[172:175], v[8:11]
	v_mfma_f32_16x16x32_bf16 v[4:7], v[188:191], v[172:175], v[4:7]
	v_mfma_f32_16x16x32_bf16 v[56:59], v[184:187], v[152:155], v[56:59]
	v_mfma_f32_16x16x32_bf16 v[48:51], v[202:205], v[152:155], v[48:51]
	v_mfma_f32_16x16x32_bf16 v[40:43], v[184:187], v[160:163], v[40:43]
	v_mfma_f32_16x16x32_bf16 v[32:35], v[202:205], v[160:163], v[32:35]
	v_mfma_f32_16x16x32_bf16 v[24:27], v[184:187], v[168:171], v[24:27]
	v_mfma_f32_16x16x32_bf16 v[16:19], v[202:205], v[168:171], v[16:19]
	v_mfma_f32_16x16x32_bf16 v[8:11], v[184:187], v[176:179], v[8:11]
	v_mfma_f32_16x16x32_bf16 v[4:7], v[202:205], v[176:179], v[4:7]
	s_barrier
	s_setprio 0

; #define PG8_STAGE(bufoff, gbase, voff) do { _Pragma("unroll") for (int _i = 0; _i < 2; ++_i) \
;         __builtin_amdgcn_global_load_lds((const unsigned*)((const char*)(gbase) + (voff)[_i]), (LAS unsigned*)(lds + (bufoff) + ldsw + _i * 8192), 16, 0, 0); } while (0)
; #define PG8_LDA(dst, b, h) do { _Pragma("unroll") for (int m = 0; m < 4; ++m) _Pragma("unroll") for (int k = 0; k < 2; ++k) dst[m][k] = *(const LAS bf16x8*)(lds + PG8_SA(b, h) + aoff + m * 2048 + k * 1024); } while (0)
; #define PG8_LDB(dst, b, h) do { _Pragma("unroll") for (int n = 0; n < 2; ++n) _Pragma("unroll") for (int k = 0; k < 2; ++k) dst[n][k] = *(const LAS bf16x8*)(lds + PG8_SB(b, h) + boff + n * 2048 + k * 1024); } while (0)
; #define PG8_WAIT_V(n) asm volatile("s_waitcnt vmcnt(" #n ")" ::: "memory")
; #define PG8_WAIT_L(n) asm volatile("s_waitcnt lgkmcnt(" #n ")" ::: "memory")
; #define PG8_BAR __builtin_amdgcn_s_barrier()
; #define PG8_SCHED __builtin_amdgcn_sched_barrier(0)
; template <class Epi, class Sched>
; __device__ __forceinline__ void gemm_phase(LAS unsigned char* lds, const Gemm g, const Sched& S, const Epi& E) {
;     ...
;         const bool has_next = S.next(ui + 1, nxt);
;         const char* nA = has_next ? (const char*)g.A + (size_t)nxt.pm * tstepA : cA; const char* nB = has_next ? (const char*)g.Bt + (size_t)nxt.pn * tstepB : cB;
;         for (int t = 0; t < nt; t += 2) {
;             const bool last = (t == nt - 2);
;             const char* a1 = cA + (size_t)(t + 1) * kstep;
;             const char* a2 = last ? nA : cA + (size_t)(t + 2) * kstep; const char* b2 = last ? nB : cB + (size_t)(t + 2) * kstep;
;             const char* a3 = a2 + kstep; const char* b3 = b2 + kstep;
;             if (last && has_next) S.a_ready(nxt);
;             PG8_LDB(B0, 0, 0); PG8_SCHED; PG8_LDA(At, 0, 0); PG8_STAGE(PG8_SA(1, 1), a1 + hstepA, voffA);
;             PG8_WAIT_L(8); PG8_BAR; PG8_WAIT_L(0); PG8_MMA(0, 0, At, B0); PG8_BAR; PG8_SCHED;
;             PG8_LDB(B1, 0, 1); PG8_STAGE(PG8_SB(0, 0), b2, voffB);
;             PG8_BAR; PG8_WAIT_L(0); PG8_MMA(0, 1, At, B1); PG8_BAR;
;             PG8_LDA(At, 0, 1); PG8_STAGE(PG8_SA(0, 0), a2, voffA);
;             PG8_BAR; PG8_WAIT_L(0); PG8_MMA(1, 0, At, B0); PG8_BAR; PG8_SCHED;
;             PG8_STAGE(PG8_SB(0, 1), b2 + hstepB, voffB);
;             PG8_WAIT_V(6); PG8_BAR; PG8_MMA(1, 1, At, B1); PG8_BAR;
.LBB0_1525:
	v_mov_b64_e32 v[4:5], 0x1600
	s_ashr_i32 s57, s56, 31
	v_cmp_lt_i64_e32 vcc, s[14:15], v[4:5]
	s_lshl_b64 s[14:15], s[56:57], 20
	s_add_u32 s58, s88, s14
	s_addc_u32 s59, s89, s15
	s_and_b64 s[14:15], vcc, exec
	s_cselect_b32 s57, s59, s5
	s_cselect_b32 s67, s58, s4
	s_ashr_i32 s55, s54, 31
	s_lshl_b64 s[14:15], s[54:55], 20
	s_add_u32 s60, s2, s14
	s_addc_u32 s61, s18, s15
	s_and_b64 s[14:15], vcc, exec
	s_cselect_b32 s55, s61, s7
	s_cselect_b32 s68, s60, s6
	s_add_u32 s4, s4, 0x80080
	s_addc_u32 s5, s5, 0
	s_add_u32 s69, s6, 0x100
	s_addc_u32 s70, s7, 0
	s_mov_b32 s71, -2
	s_setprio 0
	s_add_u32 s6, s4, 0xfff80080
	s_addc_u32 s7, s5, -1
	s_add_i32 s72, 0, 0x10000
	v_add_u32_e32 v2, s72, v1
	ds_read_b128 v[132:135], v2
	ds_read_b128 v[136:139], v2 offset:1024
	ds_read_b128 v[140:143], v2 offset:2048
	ds_read_b128 v[144:147], v2 offset:3072
	s_cmp_eq_u32 s71, 28
	s_cselect_b32 s15, s57, s7
	s_cselect_b32 s14, s67, s6
	s_cselect_b32 s7, s55, s70
	s_cselect_b32 s6, s68, s69
	ds_read_b128 v[148:151], v207
	ds_read_b128 v[152:155], v207 offset:1024
	ds_read_b128 v[156:159], v207 offset:2048
	ds_read_b128 v[160:163], v207 offset:3072
	ds_read_b128 v[164:167], v207 offset:4096
	ds_read_b128 v[168:171], v207 offset:5120
	ds_read_b128 v[186:189], v207 offset:6144
	ds_read_b128 v[190:193], v207 offset:7168
	s_add_i32 s74, 0, 0x14000
	v_add_u32_e32 v2, s74, v1
	ds_read_b128 v[194:197], v2
	ds_read_b128 v[198:201], v2 offset:1024
	ds_read_b128 v[202:205], v2 offset:2048
	ds_read_b128 v[208:211], v2 offset:3072
	s_add_i32 m0, s20, 0xc000
	s_nop 0
	global_load_lds_dwordx4 v182, s[4:5]
	s_add_i32 m0, s20, 0xe000
	s_nop 0
	global_load_lds_dwordx4 v184, s[4:5]
	s_waitcnt lgkmcnt(0)
	s_setprio 1
	s_barrier
	v_mfma_f32_16x16x32_bf16 v[68:71], v[132:135], v[148:151], 0
	v_mfma_f32_16x16x32_bf16 v[72:75], v[140:143], v[148:151], 0
	v_mfma_f32_16x16x32_bf16 v[120:123], v[132:135], v[156:159], 0
	v_mfma_f32_16x16x32_bf16 v[116:119], v[140:143], v[156:159], 0
	v_mfma_f32_16x16x32_bf16 v[112:115], v[132:135], v[164:167], 0
	v_mfma_f32_16x16x32_bf16 v[108:111], v[140:143], v[164:167], 0
	v_mfma_f32_16x16x32_bf16 v[104:107], v[132:135], v[186:189], 0
	v_mfma_f32_16x16x32_bf16 v[100:103], v[140:143], v[186:189], 0
	v_mfma_f32_16x16x32_bf16 v[68:71], v[136:139], v[152:155], v[68:71]
	v_mfma_f32_16x16x32_bf16 v[72:75], v[144:147], v[152:155], v[72:75]
	v_mfma_f32_16x16x32_bf16 v[120:123], v[136:139], v[160:163], v[120:123]
	v_mfma_f32_16x16x32_bf16 v[116:119], v[144:147], v[160:163], v[116:119]
	v_mfma_f32_16x16x32_bf16 v[112:115], v[136:139], v[168:171], v[112:115]
	v_mfma_f32_16x16x32_bf16 v[108:111], v[144:147], v[168:171], v[108:111]
	v_mfma_f32_16x16x32_bf16 v[104:107], v[136:139], v[190:193], v[104:107]
	v_mfma_f32_16x16x32_bf16 v[100:103], v[144:147], v[190:193], v[100:103]
	v_mfma_f32_16x16x32_bf16 v[76:79], v[194:197], v[148:151], 0
	v_mfma_f32_16x16x32_bf16 v[80:83], v[202:205], v[148:151], 0
	v_mfma_f32_16x16x32_bf16 v[96:99], v[194:197], v[156:159], 0
	v_mfma_f32_16x16x32_bf16 v[92:95], v[202:205], v[156:159], 0
	v_mfma_f32_16x16x32_bf16 v[88:91], v[194:197], v[164:167], 0
	v_mfma_f32_16x16x32_bf16 v[84:87], v[202:205], v[164:167], 0
	v_mfma_f32_16x16x32_bf16 v[128:131], v[194:197], v[186:189], 0
	v_mfma_f32_16x16x32_bf16 v[124:127], v[202:205], v[186:189], 0
	v_mfma_f32_16x16x32_bf16 v[76:79], v[198:201], v[152:155], v[76:79]
	v_mfma_f32_16x16x32_bf16 v[80:83], v[208:211], v[152:155], v[80:83]
	v_mfma_f32_16x16x32_bf16 v[96:99], v[198:201], v[160:163], v[96:99]
	v_mfma_f32_16x16x32_bf16 v[92:95], v[208:211], v[160:163], v[92:95]
	v_mfma_f32_16x16x32_bf16 v[88:91], v[198:201], v[168:171], v[88:91]
	v_mfma_f32_16x16x32_bf16 v[84:87], v[208:211], v[168:171], v[84:87]
	v_mfma_f32_16x16x32_bf16 v[128:131], v[198:201], v[190:193], v[128:131]
	v_mfma_f32_16x16x32_bf16 v[124:127], v[208:211], v[190:193], v[124:127]
	s_barrier
	s_setprio 0
	ds_read_b128 v[148:151], v207 offset:16384
	ds_read_b128 v[152:155], v207 offset:17408
	ds_read_b128 v[156:159], v207 offset:18432
	ds_read_b128 v[160:163], v207 offset:19456
	ds_read_b128 v[164:167], v207 offset:20480
	ds_read_b128 v[168:171], v207 offset:21504
	ds_read_b128 v[186:189], v207 offset:22528
	ds_read_b128 v[190:193], v207 offset:23552
	s_add_i32 s72, s72, s19
	v_lshl_add_u64 v[172:173], s[6:7], 0, v[178:179]
	s_mov_b32 m0, s72
	s_nop 0
	global_load_lds_dwordx4 v[172:173], off
	v_lshl_add_u64 v[212:213], s[6:7], 0, v[174:175]
	s_add_i32 m0, s72, 0x2000
	s_nop 0
	global_load_lds_dwordx4 v[212:213], off
	s_mov_b32 m0, s20
	v_lshl_add_u64 v[216:217], s[14:15], 0, v[180:181]
	global_load_lds_dwordx4 v[216:217], off
	v_lshl_add_u64 v[218:219], s[14:15], 0, v[176:177]
	s_mov_b32 m0, s21
	s_nop 0
	global_load_lds_dwordx4 v[218:219], off
	s_add_u32 s72, s6, 0x80000
	s_addc_u32 s73, s7, 0
	s_add_i32 s74, s74, s19
	s_mov_b32 m0, s74
	s_nop 0
	global_load_lds_dwordx4 v178, s[72:73]
	s_add_i32 m0, s74, 0x2000
	s_nop 0
	global_load_lds_dwordx4 v174, s[72:73]
	s_waitcnt lgkmcnt(0)
	s_waitcnt vmcnt(6)
	s_setprio 1
	s_barrier
; #define PG8_STAGE(bufoff, gbase, voff) do { _Pragma("unroll") for (int _i = 0; _i < 2; ++_i) \
;         __builtin_amdgcn_global_load_lds((const unsigned*)((const char*)(gbase) + (voff)[_i]), (LAS unsigned*)(lds + (bufoff) + ldsw + _i * 8192), 16, 0, 0); } while (0)
; #define PG8_LDA(dst, b, h) do { _Pragma("unroll") for (int m = 0; m < 4; ++m) _Pragma("unroll") for (int k = 0; k < 2; ++k) dst[m][k] = *(const LAS bf16x8*)(lds + PG8_SA(b, h) + aoff + m * 2048 + k * 1024); } while (0)
; #define PG8_LDB(dst, b, h) do { _Pragma("unroll") for (int n = 0; n < 2; ++n) _Pragma("unroll") for (int k = 0; k < 2; ++k) dst[n][k] = *(const LAS bf16x8*)(lds + PG8_SB(b, h) + boff + n * 2048 + k * 1024); } while (0)
; #define PG8_MMA(ai, bj, At, Bt) do { __builtin_amdgcn_s_setprio(1); _Pragma("unroll") for (int m = 0; m < 4; ++m) _Pragma("unroll") for (int n = 0; n < 2; ++n) _Pragma("unroll") for (int k = 0; k < 2; ++k) \
;         acc[ai][bj][m][n] = __builtin_amdgcn_mfma_f32_16x16x32_bf16(Bt[n][k], At[m][k], acc[ai][bj][m][n], 0, 0, 0); __builtin_amdgcn_s_setprio(0); } while (0)
; #define PG8_WAIT_V(n) asm volatile("s_waitcnt vmcnt(" #n ")" ::: "memory")
; #define PG8_WAIT_L(n) asm volatile("s_waitcnt lgkmcnt(" #n ")" ::: "memory")
; #define PG8_BAR __builtin_amdgcn_s_barrier()
; #define PG8_SCHED __builtin_amdgcn_sched_barrier(0)
; template <class Epi, class Sched>
; __device__ __forceinline__ void gemm_phase(LAS unsigned char* lds, const Gemm g, const Sched& S, const Epi& E) {
;     ...
;             PG8_BAR; PG8_WAIT_L(0); PG8_MMA(1, 0, At, B0); PG8_BAR; PG8_SCHED;
;             PG8_STAGE(PG8_SB(0, 1), b2 + hstepB, voffB);
;             PG8_WAIT_V(6); PG8_BAR; PG8_MMA(1, 1, At, B1); PG8_BAR;
;             PG8_LDB(B0, 1, 0); PG8_SCHED; PG8_LDA(At, 1, 0); PG8_STAGE(PG8_SA(0, 1), a2 + hstepA, voffA);
;             PG8_WAIT_L(8); PG8_BAR; PG8_WAIT_L(0); PG8_MMA(0, 0, At, B0); PG8_BAR; PG8_SCHED;
;             PG8_LDB(B1, 1, 1); PG8_STAGE(PG8_SB(1, 0), b3, voffB);
;             PG8_BAR; PG8_WAIT_L(0); PG8_MMA(0, 1, At, B1); PG8_BAR;
	v_mfma_f32_16x16x32_bf16 v[56:59], v[132:135], v[148:151], 0
	v_mfma_f32_16x16x32_bf16 v[52:55], v[140:143], v[148:151], 0
	v_mfma_f32_16x16x32_bf16 v[48:51], v[132:135], v[156:159], 0
	v_mfma_f32_16x16x32_bf16 v[44:47], v[140:143], v[156:159], 0
	v_mfma_f32_16x16x32_bf16 v[40:43], v[132:135], v[164:167], 0
	v_mfma_f32_16x16x32_bf16 v[36:39], v[140:143], v[164:167], 0
	v_mfma_f32_16x16x32_bf16 v[32:35], v[132:135], v[186:189], 0
	v_mfma_f32_16x16x32_bf16 v[28:31], v[140:143], v[186:189], 0
	v_mfma_f32_16x16x32_bf16 v[56:59], v[136:139], v[152:155], v[56:59]
	v_mfma_f32_16x16x32_bf16 v[52:55], v[144:147], v[152:155], v[52:55]
	v_mfma_f32_16x16x32_bf16 v[48:51], v[136:139], v[160:163], v[48:51]
	v_mfma_f32_16x16x32_bf16 v[44:47], v[144:147], v[160:163], v[44:47]
	v_mfma_f32_16x16x32_bf16 v[40:43], v[136:139], v[168:171], v[40:43]
	v_mfma_f32_16x16x32_bf16 v[36:39], v[144:147], v[168:171], v[36:39]
	v_mfma_f32_16x16x32_bf16 v[32:35], v[136:139], v[190:193], v[32:35]
	v_mfma_f32_16x16x32_bf16 v[28:31], v[144:147], v[190:193], v[28:31]
	v_mfma_f32_16x16x32_bf16 v[24:27], v[194:197], v[148:151], 0
	v_mfma_f32_16x16x32_bf16 v[20:23], v[202:205], v[148:151], 0
	v_mfma_f32_16x16x32_bf16 v[16:19], v[194:197], v[156:159], 0
	v_mfma_f32_16x16x32_bf16 v[12:15], v[202:205], v[156:159], 0
	v_mfma_f32_16x16x32_bf16 v[8:11], v[194:197], v[164:167], 0
	v_mfma_f32_16x16x32_bf16 v[4:7], v[202:205], v[164:167], 0
	v_mfma_f32_16x16x32_bf16 v[60:63], v[194:197], v[186:189], 0
	v_mfma_f32_16x16x32_bf16 v[64:67], v[202:205], v[186:189], 0
	v_mfma_f32_16x16x32_bf16 v[24:27], v[198:201], v[152:155], v[24:27]
	v_mfma_f32_16x16x32_bf16 v[20:23], v[208:211], v[152:155], v[20:23]
	v_mfma_f32_16x16x32_bf16 v[16:19], v[198:201], v[160:163], v[16:19]
	v_mfma_f32_16x16x32_bf16 v[12:15], v[208:211], v[160:163], v[12:15]
	v_mfma_f32_16x16x32_bf16 v[8:11], v[198:201], v[168:171], v[8:11]
	v_mfma_f32_16x16x32_bf16 v[4:7], v[208:211], v[168:171], v[4:7]
	v_mfma_f32_16x16x32_bf16 v[60:63], v[198:201], v[190:193], v[60:63]
	v_mfma_f32_16x16x32_bf16 v[64:67], v[208:211], v[190:193], v[64:67]
	s_barrier
	s_setprio 0
	s_add_i32 s72, 0, 0x18000
	v_add_u32_e32 v2, s72, v1
	ds_read_b128 v[132:135], v2
	ds_read_b128 v[136:139], v2 offset:1024
	ds_read_b128 v[140:143], v2 offset:2048
	ds_read_b128 v[144:147], v2 offset:3072
	s_add_u32 s14, s14, 0x80000
	s_addc_u32 s15, s15, 0
	ds_read_b128 v[148:151], v207 offset:32768
	ds_read_b128 v[152:155], v207 offset:33792
	ds_read_b128 v[156:159], v207 offset:34816
	ds_read_b128 v[160:163], v207 offset:35840
	ds_read_b128 v[164:167], v207 offset:36864
	ds_read_b128 v[168:171], v207 offset:37888
	ds_read_b128 v[186:189], v207 offset:38912
	ds_read_b128 v[190:193], v207 offset:39936
	s_mov_b32 m0, s24
	s_nop 0
	global_load_lds_dwordx4 v180, s[14:15]
	s_mov_b32 m0, s25
	s_nop 0
	global_load_lds_dwordx4 v176, s[14:15]
	s_add_i32 s14, 0, 0x1c000
	v_add_u32_e32 v2, s14, v1
	ds_read_b128 v[194:197], v2
	ds_read_b128 v[198:201], v2 offset:1024
	ds_read_b128 v[202:205], v2 offset:2048
	ds_read_b128 v[208:211], v2 offset:3072
	s_waitcnt lgkmcnt(0)
	s_setprio 1
	s_barrier
	v_mfma_f32_16x16x32_bf16 v[68:71], v[132:135], v[148:151], v[68:71]
	v_mfma_f32_16x16x32_bf16 v[72:75], v[140:143], v[148:151], v[72:75]
	v_mfma_f32_16x16x32_bf16 v[120:123], v[132:135], v[156:159], v[120:123]
	v_mfma_f32_16x16x32_bf16 v[116:119], v[140:143], v[156:159], v[116:119]
	v_mfma_f32_16x16x32_bf16 v[112:115], v[132:135], v[164:167], v[112:115]
	v_mfma_f32_16x16x32_bf16 v[108:111], v[140:143], v[164:167], v[108:111]
	v_mfma_f32_16x16x32_bf16 v[104:107], v[132:135], v[186:189], v[104:107]
	v_mfma_f32_16x16x32_bf16 v[100:103], v[140:143], v[186:189], v[100:103]
	v_mfma_f32_16x16x32_bf16 v[68:71], v[136:139], v[152:155], v[68:71]
	v_mfma_f32_16x16x32_bf16 v[72:75], v[144:147], v[152:155], v[72:75]
	v_mfma_f32_16x16x32_bf16 v[120:123], v[136:139], v[160:163], v[120:123]
	v_mfma_f32_16x16x32_bf16 v[116:119], v[144:147], v[160:163], v[116:119]
	v_mfma_f32_16x16x32_bf16 v[112:115], v[136:139], v[168:171], v[112:115]
	v_mfma_f32_16x16x32_bf16 v[108:111], v[144:147], v[168:171], v[108:111]
	v_mfma_f32_16x16x32_bf16 v[104:107], v[136:139], v[190:193], v[104:107]
	v_mfma_f32_16x16x32_bf16 v[100:103], v[144:147], v[190:193], v[100:103]
	v_mfma_f32_16x16x32_bf16 v[76:79], v[194:197], v[148:151], v[76:79]
	v_mfma_f32_16x16x32_bf16 v[80:83], v[202:205], v[148:151], v[80:83]
	v_mfma_f32_16x16x32_bf16 v[96:99], v[194:197], v[156:159], v[96:99]
	v_mfma_f32_16x16x32_bf16 v[92:95], v[202:205], v[156:159], v[92:95]
	v_mfma_f32_16x16x32_bf16 v[88:91], v[194:197], v[164:167], v[88:91]
	v_mfma_f32_16x16x32_bf16 v[84:87], v[202:205], v[164:167], v[84:87]
	v_mfma_f32_16x16x32_bf16 v[128:131], v[194:197], v[186:189], v[128:131]
	v_mfma_f32_16x16x32_bf16 v[124:127], v[202:205], v[186:189], v[124:127]
	v_mfma_f32_16x16x32_bf16 v[76:79], v[198:201], v[152:155], v[76:79]
	v_mfma_f32_16x16x32_bf16 v[80:83], v[208:211], v[152:155], v[80:83]
	v_mfma_f32_16x16x32_bf16 v[96:99], v[198:201], v[160:163], v[96:99]
	v_mfma_f32_16x16x32_bf16 v[92:95], v[208:211], v[160:163], v[92:95]
	v_mfma_f32_16x16x32_bf16 v[88:91], v[198:201], v[168:171], v[88:91]
	v_mfma_f32_16x16x32_bf16 v[84:87], v[208:211], v[168:171], v[84:87]
	v_mfma_f32_16x16x32_bf16 v[128:131], v[198:201], v[190:193], v[128:131]
	v_mfma_f32_16x16x32_bf16 v[124:127], v[208:211], v[190:193], v[124:127]
	s_barrier
; #define PG8_STAGE(bufoff, gbase, voff) do { _Pragma("unroll") for (int _i = 0; _i < 2; ++_i) \
;         __builtin_amdgcn_global_load_lds((const unsigned*)((const char*)(gbase) + (voff)[_i]), (LAS unsigned*)(lds + (bufoff) + ldsw + _i * 8192), 16, 0, 0); } while (0)
; #define PG8_LDA(dst, b, h) do { _Pragma("unroll") for (int m = 0; m < 4; ++m) _Pragma("unroll") for (int k = 0; k < 2; ++k) dst[m][k] = *(const LAS bf16x8*)(lds + PG8_SA(b, h) + aoff + m * 2048 + k * 1024); } while (0)
; #define PG8_LDB(dst, b, h) do { _Pragma("unroll") for (int n = 0; n < 2; ++n) _Pragma("unroll") for (int k = 0; k < 2; ++k) dst[n][k] = *(const LAS bf16x8*)(lds + PG8_SB(b, h) + boff + n * 2048 + k * 1024); } while (0)
; #define PG8_MMA(ai, bj, At, Bt) do { __builtin_amdgcn_s_setprio(1); _Pragma("unroll") for (int m = 0; m < 4; ++m) _Pragma("unroll") for (int n = 0; n < 2; ++n) _Pragma("unroll") for (int k = 0; k < 2; ++k) \
;         acc[ai][bj][m][n] = __builtin_amdgcn_mfma_f32_16x16x32_bf16(Bt[n][k], At[m][k], acc[ai][bj][m][n], 0, 0, 0); __builtin_amdgcn_s_setprio(0); } while (0)
; #define PG8_WAIT_V(n) asm volatile("s_waitcnt vmcnt(" #n ")" ::: "memory")
; #define PG8_WAIT_L(n) asm volatile("s_waitcnt lgkmcnt(" #n ")" ::: "memory")
; #define PG8_BAR __builtin_amdgcn_s_barrier()
; #define PG8_SCHED __builtin_amdgcn_sched_barrier(0)
; template <class Epi, class Sched>
; __device__ __forceinline__ void gemm_phase(LAS unsigned char* lds, const Gemm g, const Sched& S, const Epi& E) {
;     ...
;             PG8_LDB(B1, 1, 1); PG8_STAGE(PG8_SB(1, 0), b3, voffB);
;             PG8_BAR; PG8_WAIT_L(0); PG8_MMA(0, 1, At, B1); PG8_BAR;
;             PG8_LDA(At, 1, 1); PG8_STAGE(PG8_SA(1, 0), a3, voffA);
;             PG8_BAR; PG8_WAIT_L(0); PG8_MMA(1, 0, At, B0); PG8_BAR; PG8_SCHED;
;             PG8_STAGE(PG8_SB(1, 1), b3 + hstepB, voffB);
;             PG8_WAIT_V(6); PG8_BAR; PG8_MMA(1, 1, At, B1); PG8_BAR;
	s_setprio 0
	ds_read_b128 v[148:151], v207 offset:49152
	ds_read_b128 v[152:155], v207 offset:50176
	ds_read_b128 v[156:159], v207 offset:51200
	ds_read_b128 v[160:163], v207 offset:52224
	ds_read_b128 v[164:167], v207 offset:53248
	ds_read_b128 v[168:171], v207 offset:54272
	ds_read_b128 v[186:189], v207 offset:55296
	ds_read_b128 v[190:193], v207 offset:56320
	s_add_i32 s15, s72, s19
	v_lshl_add_u64 v[172:173], v[172:173], 0, s[8:9]
	s_mov_b32 m0, s15
	s_nop 0
	global_load_lds_dwordx4 v[172:173], off
	v_lshl_add_u64 v[172:173], v[212:213], 0, s[8:9]
	s_add_i32 m0, s15, 0x2000
	s_nop 0
	global_load_lds_dwordx4 v[172:173], off
	s_mov_b32 m0, s30
	v_lshl_add_u64 v[172:173], v[216:217], 0, s[8:9]
	global_load_lds_dwordx4 v[172:173], off
	v_lshl_add_u64 v[172:173], v[218:219], 0, s[8:9]
	s_mov_b32 m0, s31
	s_nop 0
	global_load_lds_dwordx4 v[172:173], off
	s_add_u32 s6, s6, 0x80080
	s_addc_u32 s7, s7, 0
	s_add_i32 s14, s14, s19
	s_mov_b32 m0, s14
	s_nop 0
	global_load_lds_dwordx4 v178, s[6:7]
	s_add_i32 m0, s14, 0x2000
	s_nop 0
	global_load_lds_dwordx4 v174, s[6:7]
	s_add_i32 s71, s71, 2
	s_add_u32 s4, s4, 0x100
	s_addc_u32 s5, s5, 0
	s_add_u32 s69, s69, 0x100
	s_addc_u32 s70, s70, 0
	s_cmp_gt_u32 s71, 29
	s_waitcnt lgkmcnt(0)
	s_waitcnt vmcnt(6)
	s_setprio 1
	s_barrier
	v_mfma_f32_16x16x32_bf16 v[56:59], v[132:135], v[148:151], v[56:59]
	v_mfma_f32_16x16x32_bf16 v[52:55], v[140:143], v[148:151], v[52:55]
	v_mfma_f32_16x16x32_bf16 v[48:51], v[132:135], v[156:159], v[48:51]
	v_mfma_f32_16x16x32_bf16 v[44:47], v[140:143], v[156:159], v[44:47]
	v_mfma_f32_16x16x32_bf16 v[40:43], v[132:135], v[164:167], v[40:43]
	v_mfma_f32_16x16x32_bf16 v[36:39], v[140:143], v[164:167], v[36:39]
	v_mfma_f32_16x16x32_bf16 v[32:35], v[132:135], v[186:189], v[32:35]
	v_mfma_f32_16x16x32_bf16 v[28:31], v[140:143], v[186:189], v[28:31]
	v_mfma_f32_16x16x32_bf16 v[56:59], v[136:139], v[152:155], v[56:59]
	v_mfma_f32_16x16x32_bf16 v[52:55], v[144:147], v[152:155], v[52:55]
	v_mfma_f32_16x16x32_bf16 v[48:51], v[136:139], v[160:163], v[48:51]
	v_mfma_f32_16x16x32_bf16 v[44:47], v[144:147], v[160:163], v[44:47]
	v_mfma_f32_16x16x32_bf16 v[40:43], v[136:139], v[168:171], v[40:43]
	v_mfma_f32_16x16x32_bf16 v[36:39], v[144:147], v[168:171], v[36:39]
	v_mfma_f32_16x16x32_bf16 v[32:35], v[136:139], v[190:193], v[32:35]
	v_mfma_f32_16x16x32_bf16 v[28:31], v[144:147], v[190:193], v[28:31]
	v_mfma_f32_16x16x32_bf16 v[24:27], v[194:197], v[148:151], v[24:27]
	v_mfma_f32_16x16x32_bf16 v[20:23], v[202:205], v[148:151], v[20:23]
	v_mfma_f32_16x16x32_bf16 v[16:19], v[194:197], v[156:159], v[16:19]
	v_mfma_f32_16x16x32_bf16 v[12:15], v[202:205], v[156:159], v[12:15]
	v_mfma_f32_16x16x32_bf16 v[8:11], v[194:197], v[164:167], v[8:11]
	v_mfma_f32_16x16x32_bf16 v[4:7], v[202:205], v[164:167], v[4:7]
	v_mfma_f32_16x16x32_bf16 v[60:63], v[194:197], v[186:189], v[60:63]
	v_mfma_f32_16x16x32_bf16 v[64:67], v[202:205], v[186:189], v[64:67]
	v_mfma_f32_16x16x32_bf16 v[24:27], v[198:201], v[152:155], v[24:27]
	v_mfma_f32_16x16x32_bf16 v[20:23], v[208:211], v[152:155], v[20:23]
	v_mfma_f32_16x16x32_bf16 v[16:19], v[198:201], v[160:163], v[16:19]
	v_mfma_f32_16x16x32_bf16 v[12:15], v[208:211], v[160:163], v[12:15]
	v_mfma_f32_16x16x32_bf16 v[8:11], v[198:201], v[168:171], v[8:11]
	v_mfma_f32_16x16x32_bf16 v[4:7], v[208:211], v[168:171], v[4:7]
	v_mfma_f32_16x16x32_bf16 v[60:63], v[198:201], v[190:193], v[60:63]
	v_mfma_f32_16x16x32_bf16 v[64:67], v[208:211], v[190:193], v[64:67]
	s_barrier
	s_setprio 0

; #define PG8_STAGE(bufoff, gbase, voff) do { _Pragma("unroll") for (int _i = 0; _i < 2; ++_i) \
;         __builtin_amdgcn_global_load_lds((const unsigned*)((const char*)(gbase) + (voff)[_i]), (LAS unsigned*)(lds + (bufoff) + ldsw + _i * 8192), 16, 0, 0); } while (0)
; #define PG8_LDA(dst, b, h) do { _Pragma("unroll") for (int m = 0; m < 4; ++m) _Pragma("unroll") for (int k = 0; k < 2; ++k) dst[m][k] = *(const LAS bf16x8*)(lds + PG8_SA(b, h) + aoff + m * 2048 + k * 1024); } while (0)
; #define PG8_LDB(dst, b, h) do { _Pragma("unroll") for (int n = 0; n < 2; ++n) _Pragma("unroll") for (int k = 0; k < 2; ++k) dst[n][k] = *(const LAS bf16x8*)(lds + PG8_SB(b, h) + boff + n * 2048 + k * 1024); } while (0)
; #define PG8_MMA(ai, bj, At, Bt) do { __builtin_amdgcn_s_setprio(1); _Pragma("unroll") for (int m = 0; m < 4; ++m) _Pragma("unroll") for (int n = 0; n < 2; ++n) _Pragma("unroll") for (int k = 0; k < 2; ++k) \
;         acc[ai][bj][m][n] = __builtin_amdgcn_mfma_f32_16x16x32_bf16(Bt[n][k], At[m][k], acc[ai][bj][m][n], 0, 0, 0); __builtin_amdgcn_s_setprio(0); } while (0)
; #define PG8_WAIT_V(n) asm volatile("s_waitcnt vmcnt(" #n ")" ::: "memory")
; #define PG8_WAIT_L(n) asm volatile("s_waitcnt lgkmcnt(" #n ")" ::: "memory")
; #define PG8_BAR __builtin_amdgcn_s_barrier()
; #define PG8_SCHED __builtin_amdgcn_sched_barrier(0)
; template <class Epi, class Sched>
; __device__ __forceinline__ void gemm_phase(LAS unsigned char* lds, const Gemm g, const Sched& S, const Epi& E) {
;     ...
;             PG8_LDB(B0, 0, 0); PG8_SCHED; PG8_LDA(At, 0, 0); PG8_STAGE(PG8_SA(1, 1), a1 + hstepA, voffA);
;             PG8_WAIT_L(8); PG8_BAR; PG8_WAIT_L(0); PG8_MMA(0, 0, At, B0); PG8_BAR; PG8_SCHED;
;             PG8_LDB(B1, 0, 1); PG8_STAGE(PG8_SB(0, 0), b2, voffB);
;             PG8_BAR; PG8_WAIT_L(0); PG8_MMA(0, 1, At, B1); PG8_BAR;
;             PG8_LDA(At, 0, 1); PG8_STAGE(PG8_SA(0, 0), a2, voffA);
;             PG8_BAR; PG8_WAIT_L(0); PG8_MMA(1, 0, At, B0); PG8_BAR; PG8_SCHED;
;             PG8_STAGE(PG8_SB(0, 1), b2 + hstepB, voffB);
;             PG8_WAIT_V(6); PG8_BAR; PG8_MMA(1, 1, At, B1); PG8_BAR;
.LBB0_1665:
	s_add_u32 s42, s14, 0x100
	s_addc_u32 s43, s15, 0
	s_mov_b32 s44, -2
	s_setprio 0
	s_add_u32 s14, s6, 0x100
	s_addc_u32 s15, s7, 0
	s_add_i32 s45, 0, 0x10000
	v_add_u32_e32 v144, s45, v1
	ds_read_b128 v[132:135], v144
	ds_read_b128 v[136:139], v144 offset:1024
	ds_read_b128 v[140:143], v144 offset:2048
	ds_read_b128 v[144:147], v144 offset:3072
	s_cmpk_eq_i32 s44, 0x54
	s_cselect_b32 s21, s1, s15
	s_cselect_b32 s20, s0, s14
	s_cselect_b32 s19, s5, s43
	s_cselect_b32 s18, s4, s42
	ds_read_b128 v[148:151], v224
	ds_read_b128 v[152:155], v224 offset:1024
	ds_read_b128 v[156:159], v224 offset:2048
	ds_read_b128 v[160:163], v224 offset:3072
	ds_read_b128 v[164:167], v224 offset:4096
	ds_read_b128 v[168:171], v224 offset:5120
	ds_read_b128 v[172:175], v224 offset:6144
	ds_read_b128 v[176:179], v224 offset:7168
	s_add_i32 s51, 0, 0x14000
	v_add_u32_e32 v202, s51, v1
	ds_read_b128 v[180:183], v202
	ds_read_b128 v[184:187], v202 offset:1024
	ds_read_b128 v[188:191], v202 offset:2048
	ds_read_b128 v[202:205], v202 offset:3072
	s_add_i32 m0, s29, 0xc000
	s_nop 0
	global_load_lds_dwordx4 v198, s[6:7]
	s_add_i32 m0, s29, 0xe000
	s_nop 0
	global_load_lds_dwordx4 v200, s[6:7]
	s_waitcnt lgkmcnt(0)
	s_setprio 1
	s_barrier
	v_mfma_f32_16x16x32_bf16 v[128:131], v[132:135], v[148:151], 0
	v_mfma_f32_16x16x32_bf16 v[124:127], v[140:143], v[148:151], 0
	v_mfma_f32_16x16x32_bf16 v[112:115], v[132:135], v[156:159], 0
	v_mfma_f32_16x16x32_bf16 v[108:111], v[140:143], v[156:159], 0
	v_mfma_f32_16x16x32_bf16 v[100:103], v[132:135], v[164:167], 0
	v_mfma_f32_16x16x32_bf16 v[92:95], v[140:143], v[164:167], 0
	v_mfma_f32_16x16x32_bf16 v[84:87], v[132:135], v[172:175], 0
	v_mfma_f32_16x16x32_bf16 v[76:79], v[140:143], v[172:175], 0
	v_mfma_f32_16x16x32_bf16 v[128:131], v[136:139], v[152:155], v[128:131]
	v_mfma_f32_16x16x32_bf16 v[124:127], v[144:147], v[152:155], v[124:127]
	v_mfma_f32_16x16x32_bf16 v[112:115], v[136:139], v[160:163], v[112:115]
	v_mfma_f32_16x16x32_bf16 v[108:111], v[144:147], v[160:163], v[108:111]
	v_mfma_f32_16x16x32_bf16 v[100:103], v[136:139], v[168:171], v[100:103]
	v_mfma_f32_16x16x32_bf16 v[92:95], v[144:147], v[168:171], v[92:95]
	v_mfma_f32_16x16x32_bf16 v[84:87], v[136:139], v[176:179], v[84:87]
	v_mfma_f32_16x16x32_bf16 v[76:79], v[144:147], v[176:179], v[76:79]
	v_mfma_f32_16x16x32_bf16 v[120:123], v[180:183], v[148:151], 0
	v_mfma_f32_16x16x32_bf16 v[116:119], v[188:191], v[148:151], 0
	v_mfma_f32_16x16x32_bf16 v[104:107], v[180:183], v[156:159], 0
	v_mfma_f32_16x16x32_bf16 v[96:99], v[188:191], v[156:159], 0
	v_mfma_f32_16x16x32_bf16 v[88:91], v[180:183], v[164:167], 0
	v_mfma_f32_16x16x32_bf16 v[80:83], v[188:191], v[164:167], 0
	v_mfma_f32_16x16x32_bf16 v[72:75], v[180:183], v[172:175], 0
	v_mfma_f32_16x16x32_bf16 v[68:71], v[188:191], v[172:175], 0
	v_mfma_f32_16x16x32_bf16 v[120:123], v[184:187], v[152:155], v[120:123]
	v_mfma_f32_16x16x32_bf16 v[116:119], v[202:205], v[152:155], v[116:119]
	v_mfma_f32_16x16x32_bf16 v[104:107], v[184:187], v[160:163], v[104:107]
	v_mfma_f32_16x16x32_bf16 v[96:99], v[202:205], v[160:163], v[96:99]
	v_mfma_f32_16x16x32_bf16 v[88:91], v[184:187], v[168:171], v[88:91]
	v_mfma_f32_16x16x32_bf16 v[80:83], v[202:205], v[168:171], v[80:83]
	v_mfma_f32_16x16x32_bf16 v[72:75], v[184:187], v[176:179], v[72:75]
	v_mfma_f32_16x16x32_bf16 v[68:71], v[202:205], v[176:179], v[68:71]
	s_barrier
	s_setprio 0
	ds_read_b128 v[148:151], v224 offset:16384
	ds_read_b128 v[152:155], v224 offset:17408
	ds_read_b128 v[156:159], v224 offset:18432
	ds_read_b128 v[160:163], v224 offset:19456
	ds_read_b128 v[164:167], v224 offset:20480
	ds_read_b128 v[168:171], v224 offset:21504
	ds_read_b128 v[172:175], v224 offset:22528
	ds_read_b128 v[176:179], v224 offset:23552
	s_add_i32 s6, s45, s28
	v_lshl_add_u64 v[206:207], s[18:19], 0, v[2:3]
	s_mov_b32 m0, s6
	s_nop 0
	global_load_lds_dwordx4 v[206:207], off
	v_lshl_add_u64 v[208:209], s[18:19], 0, v[192:193]
	s_add_i32 m0, s6, 0x2000
	s_nop 0
	global_load_lds_dwordx4 v[208:209], off
	s_mov_b32 m0, s29
	v_lshl_add_u64 v[210:211], s[20:21], 0, v[196:197]
	global_load_lds_dwordx4 v[210:211], off
	v_lshl_add_u64 v[212:213], s[20:21], 0, v[194:195]
	s_mov_b32 m0, s30
	s_nop 0
	global_load_lds_dwordx4 v[212:213], off
	s_add_u32 s6, s18, 0x160000
	s_addc_u32 s7, s19, 0
	s_add_i32 s45, s51, s28
	s_mov_b32 m0, s45
	s_nop 0
	global_load_lds_dwordx4 v2, s[6:7]
	s_add_i32 m0, s45, 0x2000
	s_nop 0
	global_load_lds_dwordx4 v192, s[6:7]
	s_waitcnt lgkmcnt(0)
	s_waitcnt vmcnt(6)
	s_setprio 1
	s_barrier
	v_mfma_f32_16x16x32_bf16 v[64:67], v[132:135], v[148:151], 0
	v_mfma_f32_16x16x32_bf16 v[60:63], v[140:143], v[148:151], 0
	v_mfma_f32_16x16x32_bf16 v[52:55], v[132:135], v[156:159], 0
	v_mfma_f32_16x16x32_bf16 v[44:47], v[140:143], v[156:159], 0
	v_mfma_f32_16x16x32_bf16 v[36:39], v[132:135], v[164:167], 0
	v_mfma_f32_16x16x32_bf16 v[28:31], v[140:143], v[164:167], 0
	v_mfma_f32_16x16x32_bf16 v[20:23], v[132:135], v[172:175], 0
	v_mfma_f32_16x16x32_bf16 v[12:15], v[140:143], v[172:175], 0
	v_mfma_f32_16x16x32_bf16 v[64:67], v[136:139], v[152:155], v[64:67]
	v_mfma_f32_16x16x32_bf16 v[60:63], v[144:147], v[152:155], v[60:63]
	v_mfma_f32_16x16x32_bf16 v[52:55], v[136:139], v[160:163], v[52:55]
	v_mfma_f32_16x16x32_bf16 v[44:47], v[144:147], v[160:163], v[44:47]
	v_mfma_f32_16x16x32_bf16 v[36:39], v[136:139], v[168:171], v[36:39]
	v_mfma_f32_16x16x32_bf16 v[28:31], v[144:147], v[168:171], v[28:31]
	v_mfma_f32_16x16x32_bf16 v[20:23], v[136:139], v[176:179], v[20:23]
	v_mfma_f32_16x16x32_bf16 v[12:15], v[144:147], v[176:179], v[12:15]
	v_mfma_f32_16x16x32_bf16 v[56:59], v[180:183], v[148:151], 0
	v_mfma_f32_16x16x32_bf16 v[48:51], v[188:191], v[148:151], 0
	v_mfma_f32_16x16x32_bf16 v[40:43], v[180:183], v[156:159], 0
	v_mfma_f32_16x16x32_bf16 v[32:35], v[188:191], v[156:159], 0
	v_mfma_f32_16x16x32_bf16 v[24:27], v[180:183], v[164:167], 0
	v_mfma_f32_16x16x32_bf16 v[16:19], v[188:191], v[164:167], 0
	v_mfma_f32_16x16x32_bf16 v[8:11], v[180:183], v[172:175], 0
	v_mfma_f32_16x16x32_bf16 v[4:7], v[188:191], v[172:175], 0
	v_mfma_f32_16x16x32_bf16 v[56:59], v[184:187], v[152:155], v[56:59]
	v_mfma_f32_16x16x32_bf16 v[48:51], v[202:205], v[152:155], v[48:51]
	v_mfma_f32_16x16x32_bf16 v[40:43], v[184:187], v[160:163], v[40:43]
	v_mfma_f32_16x16x32_bf16 v[32:35], v[202:205], v[160:163], v[32:35]
	v_mfma_f32_16x16x32_bf16 v[24:27], v[184:187], v[168:171], v[24:27]
	v_mfma_f32_16x16x32_bf16 v[16:19], v[202:205], v[168:171], v[16:19]
	v_mfma_f32_16x16x32_bf16 v[8:11], v[184:187], v[176:179], v[8:11]
	v_mfma_f32_16x16x32_bf16 v[4:7], v[202:205], v[176:179], v[4:7]
	s_barrier
; #define PG8_STAGE(bufoff, gbase, voff) do { _Pragma("unroll") for (int _i = 0; _i < 2; ++_i) \
;         __builtin_amdgcn_global_load_lds((const unsigned*)((const char*)(gbase) + (voff)[_i]), (LAS unsigned*)(lds + (bufoff) + ldsw + _i * 8192), 16, 0, 0); } while (0)
; #define PG8_LDA(dst, b, h) do { _Pragma("unroll") for (int m = 0; m < 4; ++m) _Pragma("unroll") for (int k = 0; k < 2; ++k) dst[m][k] = *(const LAS bf16x8*)(lds + PG8_SA(b, h) + aoff + m * 2048 + k * 1024); } while (0)
; #define PG8_LDB(dst, b, h) do { _Pragma("unroll") for (int n = 0; n < 2; ++n) _Pragma("unroll") for (int k = 0; k < 2; ++k) dst[n][k] = *(const LAS bf16x8*)(lds + PG8_SB(b, h) + boff + n * 2048 + k * 1024); } while (0)
; #define PG8_MMA(ai, bj, At, Bt) do { __builtin_amdgcn_s_setprio(1); _Pragma("unroll") for (int m = 0; m < 4; ++m) _Pragma("unroll") for (int n = 0; n < 2; ++n) _Pragma("unroll") for (int k = 0; k < 2; ++k) \
;         acc[ai][bj][m][n] = __builtin_amdgcn_mfma_f32_16x16x32_bf16(Bt[n][k], At[m][k], acc[ai][bj][m][n], 0, 0, 0); __builtin_amdgcn_s_setprio(0); } while (0)
; #define PG8_WAIT_V(n) asm volatile("s_waitcnt vmcnt(" #n ")" ::: "memory")
; #define PG8_WAIT_L(n) asm volatile("s_waitcnt lgkmcnt(" #n ")" ::: "memory")
; #define PG8_BAR __builtin_amdgcn_s_barrier()
; #define PG8_SCHED __builtin_amdgcn_sched_barrier(0)
; template <class Epi, class Sched>
; __device__ __forceinline__ void gemm_phase(LAS unsigned char* lds, const Gemm g, const Sched& S, const Epi& E) {
;     ...
;             PG8_LDB(B0, 1, 0); PG8_SCHED; PG8_LDA(At, 1, 0); PG8_STAGE(PG8_SA(0, 1), a2 + hstepA, voffA);
;             PG8_WAIT_L(8); PG8_BAR; PG8_WAIT_L(0); PG8_MMA(0, 0, At, B0); PG8_BAR; PG8_SCHED;
;             PG8_LDB(B1, 1, 1); PG8_STAGE(PG8_SB(1, 0), b3, voffB);
;             PG8_BAR; PG8_WAIT_L(0); PG8_MMA(0, 1, At, B1); PG8_BAR;
;             PG8_LDA(At, 1, 1); PG8_STAGE(PG8_SA(1, 0), a3, voffA);
;             PG8_BAR; PG8_WAIT_L(0); PG8_MMA(1, 0, At, B0); PG8_BAR; PG8_SCHED;
;             PG8_STAGE(PG8_SB(1, 1), b3 + hstepB, voffB);
;             PG8_WAIT_V(6); PG8_BAR; PG8_MMA(1, 1, At, B1); PG8_BAR;
	s_setprio 0
	s_add_i32 s45, 0, 0x18000
	v_add_u32_e32 v144, s45, v1
	ds_read_b128 v[132:135], v144
	ds_read_b128 v[136:139], v144 offset:1024
	ds_read_b128 v[140:143], v144 offset:2048
	ds_read_b128 v[144:147], v144 offset:3072
	s_add_u32 s6, s20, 0x160000
	s_addc_u32 s7, s21, 0
	ds_read_b128 v[148:151], v224 offset:32768
	ds_read_b128 v[152:155], v224 offset:33792
	ds_read_b128 v[156:159], v224 offset:34816
	ds_read_b128 v[160:163], v224 offset:35840
	ds_read_b128 v[164:167], v224 offset:36864
	ds_read_b128 v[168:171], v224 offset:37888
	ds_read_b128 v[172:175], v224 offset:38912
	ds_read_b128 v[176:179], v224 offset:39936
	s_mov_b32 m0, s31
	s_nop 0
	global_load_lds_dwordx4 v196, s[6:7]
	s_mov_b32 m0, s35
	s_nop 0
	global_load_lds_dwordx4 v194, s[6:7]
	s_add_i32 s20, 0, 0x1c000
	v_add_u32_e32 v202, s20, v1
	ds_read_b128 v[180:183], v202
	ds_read_b128 v[184:187], v202 offset:1024
	ds_read_b128 v[188:191], v202 offset:2048
	ds_read_b128 v[202:205], v202 offset:3072
	s_waitcnt lgkmcnt(0)
	s_setprio 1
	s_barrier
	v_mfma_f32_16x16x32_bf16 v[128:131], v[132:135], v[148:151], v[128:131]
	v_mfma_f32_16x16x32_bf16 v[124:127], v[140:143], v[148:151], v[124:127]
	v_mfma_f32_16x16x32_bf16 v[112:115], v[132:135], v[156:159], v[112:115]
	v_mfma_f32_16x16x32_bf16 v[108:111], v[140:143], v[156:159], v[108:111]
	v_mfma_f32_16x16x32_bf16 v[100:103], v[132:135], v[164:167], v[100:103]
	v_mfma_f32_16x16x32_bf16 v[92:95], v[140:143], v[164:167], v[92:95]
	v_mfma_f32_16x16x32_bf16 v[84:87], v[132:135], v[172:175], v[84:87]
	v_mfma_f32_16x16x32_bf16 v[76:79], v[140:143], v[172:175], v[76:79]
	v_mfma_f32_16x16x32_bf16 v[128:131], v[136:139], v[152:155], v[128:131]
	v_mfma_f32_16x16x32_bf16 v[124:127], v[144:147], v[152:155], v[124:127]
	v_mfma_f32_16x16x32_bf16 v[112:115], v[136:139], v[160:163], v[112:115]
	v_mfma_f32_16x16x32_bf16 v[108:111], v[144:147], v[160:163], v[108:111]
	v_mfma_f32_16x16x32_bf16 v[100:103], v[136:139], v[168:171], v[100:103]
	v_mfma_f32_16x16x32_bf16 v[92:95], v[144:147], v[168:171], v[92:95]
	v_mfma_f32_16x16x32_bf16 v[84:87], v[136:139], v[176:179], v[84:87]
	v_mfma_f32_16x16x32_bf16 v[76:79], v[144:147], v[176:179], v[76:79]
	v_mfma_f32_16x16x32_bf16 v[120:123], v[180:183], v[148:151], v[120:123]
	v_mfma_f32_16x16x32_bf16 v[116:119], v[188:191], v[148:151], v[116:119]
	v_mfma_f32_16x16x32_bf16 v[104:107], v[180:183], v[156:159], v[104:107]
	v_mfma_f32_16x16x32_bf16 v[96:99], v[188:191], v[156:159], v[96:99]
	v_mfma_f32_16x16x32_bf16 v[88:91], v[180:183], v[164:167], v[88:91]
	v_mfma_f32_16x16x32_bf16 v[80:83], v[188:191], v[164:167], v[80:83]
	v_mfma_f32_16x16x32_bf16 v[72:75], v[180:183], v[172:175], v[72:75]
	v_mfma_f32_16x16x32_bf16 v[68:71], v[188:191], v[172:175], v[68:71]
	v_mfma_f32_16x16x32_bf16 v[120:123], v[184:187], v[152:155], v[120:123]
	v_mfma_f32_16x16x32_bf16 v[116:119], v[202:205], v[152:155], v[116:119]
	v_mfma_f32_16x16x32_bf16 v[104:107], v[184:187], v[160:163], v[104:107]
	v_mfma_f32_16x16x32_bf16 v[96:99], v[202:205], v[160:163], v[96:99]
	v_mfma_f32_16x16x32_bf16 v[88:91], v[184:187], v[168:171], v[88:91]
	v_mfma_f32_16x16x32_bf16 v[80:83], v[202:205], v[168:171], v[80:83]
	v_mfma_f32_16x16x32_bf16 v[72:75], v[184:187], v[176:179], v[72:75]
	v_mfma_f32_16x16x32_bf16 v[68:71], v[202:205], v[176:179], v[68:71]
	s_barrier
	s_setprio 0
	ds_read_b128 v[148:151], v224 offset:49152
	ds_read_b128 v[152:155], v224 offset:50176
	ds_read_b128 v[156:159], v224 offset:51200
	ds_read_b128 v[160:163], v224 offset:52224
	ds_read_b128 v[164:167], v224 offset:53248
	ds_read_b128 v[168:171], v224 offset:54272
	ds_read_b128 v[172:175], v224 offset:55296
	ds_read_b128 v[176:179], v224 offset:56320
	s_add_i32 s6, s45, s28
	v_lshl_add_u64 v[206:207], v[206:207], 0, s[8:9]
	s_mov_b32 m0, s6
	s_nop 0
	global_load_lds_dwordx4 v[206:207], off
	v_lshl_add_u64 v[206:207], v[208:209], 0, s[8:9]
	s_add_i32 m0, s6, 0x2000
	s_nop 0
	global_load_lds_dwordx4 v[206:207], off
	s_mov_b32 m0, s38
	v_lshl_add_u64 v[206:207], v[210:211], 0, s[8:9]
	global_load_lds_dwordx4 v[206:207], off
	v_lshl_add_u64 v[206:207], v[212:213], 0, s[8:9]
	s_mov_b32 m0, s39
	s_nop 0
	global_load_lds_dwordx4 v[206:207], off
	s_add_u32 s6, s18, 0x160080
	s_addc_u32 s7, s19, 0
	s_add_i32 s18, s20, s28
	s_mov_b32 m0, s18
	s_nop 0
	global_load_lds_dwordx4 v2, s[6:7]
	s_add_i32 m0, s18, 0x2000
	s_nop 0
	global_load_lds_dwordx4 v192, s[6:7]
	s_add_i32 s44, s44, 2
	s_add_u32 s42, s42, 0x100
	s_addc_u32 s43, s43, 0
	s_cmpk_gt_u32 s44, 0x55
	s_mov_b64 s[6:7], s[14:15]
	s_waitcnt lgkmcnt(0)
	s_waitcnt vmcnt(6)
	s_setprio 1
	s_barrier
	v_mfma_f32_16x16x32_bf16 v[64:67], v[132:135], v[148:151], v[64:67]
	v_mfma_f32_16x16x32_bf16 v[60:63], v[140:143], v[148:151], v[60:63]
	v_mfma_f32_16x16x32_bf16 v[52:55], v[132:135], v[156:159], v[52:55]
	v_mfma_f32_16x16x32_bf16 v[44:47], v[140:143], v[156:159], v[44:47]
	v_mfma_f32_16x16x32_bf16 v[36:39], v[132:135], v[164:167], v[36:39]
	v_mfma_f32_16x16x32_bf16 v[28:31], v[140:143], v[164:167], v[28:31]
	v_mfma_f32_16x16x32_bf16 v[20:23], v[132:135], v[172:175], v[20:23]
	v_mfma_f32_16x16x32_bf16 v[12:15], v[140:143], v[172:175], v[12:15]
	v_mfma_f32_16x16x32_bf16 v[64:67], v[136:139], v[152:155], v[64:67]
	v_mfma_f32_16x16x32_bf16 v[60:63], v[144:147], v[152:155], v[60:63]
	v_mfma_f32_16x16x32_bf16 v[52:55], v[136:139], v[160:163], v[52:55]
	v_mfma_f32_16x16x32_bf16 v[44:47], v[144:147], v[160:163], v[44:47]
	v_mfma_f32_16x16x32_bf16 v[36:39], v[136:139], v[168:171], v[36:39]
	v_mfma_f32_16x16x32_bf16 v[28:31], v[144:147], v[168:171], v[28:31]
	v_mfma_f32_16x16x32_bf16 v[20:23], v[136:139], v[176:179], v[20:23]
	v_mfma_f32_16x16x32_bf16 v[12:15], v[144:147], v[176:179], v[12:15]
	v_mfma_f32_16x16x32_bf16 v[56:59], v[180:183], v[148:151], v[56:59]
	v_mfma_f32_16x16x32_bf16 v[48:51], v[188:191], v[148:151], v[48:51]
	v_mfma_f32_16x16x32_bf16 v[40:43], v[180:183], v[156:159], v[40:43]
	v_mfma_f32_16x16x32_bf16 v[32:35], v[188:191], v[156:159], v[32:35]
	v_mfma_f32_16x16x32_bf16 v[24:27], v[180:183], v[164:167], v[24:27]
	v_mfma_f32_16x16x32_bf16 v[16:19], v[188:191], v[164:167], v[16:19]
	v_mfma_f32_16x16x32_bf16 v[8:11], v[180:183], v[172:175], v[8:11]
	v_mfma_f32_16x16x32_bf16 v[4:7], v[188:191], v[172:175], v[4:7]
	v_mfma_f32_16x16x32_bf16 v[56:59], v[184:187], v[152:155], v[56:59]
	v_mfma_f32_16x16x32_bf16 v[48:51], v[202:205], v[152:155], v[48:51]
	v_mfma_f32_16x16x32_bf16 v[40:43], v[184:187], v[160:163], v[40:43]
	v_mfma_f32_16x16x32_bf16 v[32:35], v[202:205], v[160:163], v[32:35]
	v_mfma_f32_16x16x32_bf16 v[24:27], v[184:187], v[168:171], v[24:27]
	v_mfma_f32_16x16x32_bf16 v[16:19], v[202:205], v[168:171], v[16:19]
	v_mfma_f32_16x16x32_bf16 v[8:11], v[184:187], v[176:179], v[8:11]
	v_mfma_f32_16x16x32_bf16 v[4:7], v[202:205], v[176:179], v[4:7]
	s_barrier
	s_setprio 0
